# P5b and P7b elementwise phases rewritten: next row's loads in flight, counted vmcnt, gains in registers, DPP row reduction
# speedup vs baseline: 1.0110x; 1.0096x over previous
; #define INP(i) ((const float*)(const GAS float*)KARG(8 * (i)))
; #define X_IN INP(0)
; __global__ void __launch_bounds__(512, 2) fwd(Params P) {
;     ...
;     if (PHASE_MASK & (1 << 6)) {
;         const f32x4* g1 = (const f32x4*)INP(12) + lane; const f32x4* g2 = (const f32x4*)INP(13) + lane;
;         for (int m = gw; m < T_TOK; m += NGW) {
;             const float rsy = __builtin_amdgcn_rsqf(ssq_y[m] * (1.f / DM) + EPS);
;             const f32x4* xr = (const f32x4*)(X_IN + (size_t)m * DM) + lane; const u32x2* yr = (const u32x2*)(YB + (size_t)m * DM) + lane;
;             f32x4* orow = (f32x4*)(OUT_P + (size_t)m * DM) + lane;
;             f32x4 v[8]; float s = 0.f;
; #pragma unroll
;             for (int j = 0; j < 8; ++j) { const f32x4 xv = __builtin_nontemporal_load(&xr[64 * j]); const u32x2 yw = __builtin_nontemporal_load(&yr[64 * j]); const f32x4 g = g1[64 * j];
.LBB0_1226:
	s_or_b64 exec, exec, s[6:7]
	v_readlane_b32 s12, v246, 4
	v_readlane_b32 s13, v246, 5
	s_mov_b64 s[8:9], s[0:1]
	s_mov_b64 s[10:11], s[0:1]
	s_waitcnt lgkmcnt(0)
	v_cndmask_b32_e64 v0, 0, 1, s[12:13]
	v_cmp_ne_u32_e64 s[6:7], 1, v0
	s_andn2_b64 vcc, exec, s[12:13]
	s_barrier
	s_cbranch_vccnz .LBB0_1229
	s_load_dwordx2 s[8:9], s[0:1], 0x0
	s_load_dwordx2 s[10:11], s[0:1], 0xa8
	s_load_dwordx2 s[18:19], s[0:1], 0xa0
	s_load_dwordx2 s[20:21], s[0:1], 0x8
	s_load_dwordx2 s[24:25], s[0:1], 0x60
	s_load_dwordx2 s[26:27], s[0:1], 0x68
	v_mov_b32_e32 v167, 0
	v_lshlrev_b32_e32 v181, 3, v179
	v_mov_b32_e32 v182, 0x358637bd
	s_mov_b32 s30, s80
	s_waitcnt lgkmcnt(0)
	s_add_u32 s8, s8, 0x1000
	s_addc_u32 s9, s9, 0
	s_add_u32 s18, s18, 0x1000
	s_addc_u32 s19, s19, 0
	s_add_u32 s12, s10, 0x40000
	s_addc_u32 s13, s11, 0
	s_add_u32 s14, s10, 0x18000000
	s_addc_u32 s15, s11, 0
	s_add_u32 s16, s10, 0x8000000
	s_addc_u32 s17, s11, 0
	s_add_u32 s22, s10, 0x30000000
	s_addc_u32 s23, s11, 0
	s_add_u32 s28, s24, 0x1000
	s_addc_u32 s29, s25, 0
	s_add_u32 s34, s26, 0x1000
	s_addc_u32 s35, s27, 0
	global_load_dwordx4 v[0:3], v166, s[24:25] offset:0
	global_load_dwordx4 v[4:7], v166, s[24:25] offset:1024
	global_load_dwordx4 v[8:11], v166, s[24:25] offset:2048
	global_load_dwordx4 v[12:15], v166, s[24:25] offset:3072
	global_load_dwordx4 v[16:19], v166, s[28:29] offset:0
	global_load_dwordx4 v[20:23], v166, s[28:29] offset:1024
	global_load_dwordx4 v[24:27], v166, s[28:29] offset:2048
	global_load_dwordx4 v[28:31], v166, s[28:29] offset:3072
	global_load_dwordx4 v[32:35], v166, s[26:27] offset:0
	global_load_dwordx4 v[36:39], v166, s[26:27] offset:1024
	global_load_dwordx4 v[40:43], v166, s[26:27] offset:2048
	global_load_dwordx4 v[44:47], v166, s[26:27] offset:3072
	global_load_dwordx4 v[48:51], v166, s[34:35] offset:0
	global_load_dwordx4 v[52:55], v166, s[34:35] offset:1024
	global_load_dwordx4 v[56:59], v166, s[34:35] offset:2048
	global_load_dwordx4 v[60:63], v166, s[34:35] offset:3072
	s_lshl_b32 s2, s30, 13
	s_add_u32 s24, s8, s2
	s_addc_u32 s25, s9, 0
	s_lshl_b32 s2, s30, 12
	s_add_u32 s26, s14, s2
	s_addc_u32 s27, s15, 0
	s_lshl_b32 s2, s30, 2
	s_add_u32 s28, s12, s2
	s_addc_u32 s29, s13, 0
	s_lshl_b32 s2, s30, 10
	s_add_u32 s34, s20, s2
	s_addc_u32 s35, s21, 0
	global_load_dword v112, v167, s[28:29]
	global_load_dwordx4 v[64:67], v166, s[24:25] offset:-4096 nt
	global_load_dwordx2 v[96:97], v181, s[26:27] offset:0 nt
	global_load_dwordx4 v[68:71], v166, s[24:25] offset:-3072 nt
	global_load_dwordx2 v[98:99], v181, s[26:27] offset:512 nt
	global_load_dwordx4 v[72:75], v166, s[24:25] offset:-2048 nt
	global_load_dwordx2 v[100:101], v181, s[26:27] offset:1024 nt
	global_load_dwordx4 v[76:79], v166, s[24:25] offset:-1024 nt
	global_load_dwordx2 v[102:103], v181, s[26:27] offset:1536 nt
	global_load_dwordx4 v[80:83], v166, s[24:25] offset:0 nt
	global_load_dwordx2 v[104:105], v181, s[26:27] offset:2048 nt
	global_load_dwordx4 v[84:87], v166, s[24:25] offset:1024 nt
	global_load_dwordx2 v[106:107], v181, s[26:27] offset:2560 nt
	global_load_dwordx4 v[88:91], v166, s[24:25] offset:2048 nt
	global_load_dwordx2 v[108:109], v181, s[26:27] offset:3072 nt
	global_load_dwordx4 v[92:95], v166, s[24:25] offset:3072 nt
	global_load_dwordx2 v[110:111], v181, s[26:27] offset:3584 nt
	global_load_dwordx4 v[114:117], v166, s[34:35]
	s_lshl_b32 s2, s30, 13
	s_add_u32 s36, s18, s2
	s_addc_u32 s37, s19, 0
	s_lshl_b32 s2, s30, 12
	s_add_u32 s38, s16, s2
	s_addc_u32 s39, s17, 0
	s_lshl_b32 s2, s30, 9
	s_add_u32 s40, s22, s2
	s_addc_u32 s41, s23, 0
	s_add_i32 s10, s30, s82
	s_cmpk_gt_i32 s10, 0x7fff
	s_cselect_b32 s10, s30, s10
	s_lshl_b32 s2, s10, 13
	s_add_u32 s24, s8, s2
	s_addc_u32 s25, s9, 0
	s_lshl_b32 s2, s10, 12
	s_add_u32 s26, s14, s2
	s_addc_u32 s27, s15, 0
	s_lshl_b32 s2, s10, 2
	s_add_u32 s28, s12, s2
	s_addc_u32 s29, s13, 0
	s_lshl_b32 s2, s10, 10
	s_add_u32 s34, s20, s2
	s_addc_u32 s35, s21, 0
	global_load_dword v168, v167, s[28:29]
	global_load_dwordx4 v[118:121], v166, s[24:25] offset:-4096 nt
	global_load_dwordx2 v[150:151], v181, s[26:27] offset:0 nt
	global_load_dwordx4 v[122:125], v166, s[24:25] offset:-3072 nt
	global_load_dwordx2 v[152:153], v181, s[26:27] offset:512 nt
	global_load_dwordx4 v[126:129], v166, s[24:25] offset:-2048 nt
	global_load_dwordx2 v[154:155], v181, s[26:27] offset:1024 nt
	global_load_dwordx4 v[130:133], v166, s[24:25] offset:-1024 nt
	global_load_dwordx2 v[156:157], v181, s[26:27] offset:1536 nt
	global_load_dwordx4 v[134:137], v166, s[24:25] offset:0 nt
	global_load_dwordx2 v[158:159], v181, s[26:27] offset:2048 nt
	global_load_dwordx4 v[138:141], v166, s[24:25] offset:1024 nt
	global_load_dwordx2 v[160:161], v181, s[26:27] offset:2560 nt
	global_load_dwordx4 v[142:145], v166, s[24:25] offset:2048 nt
	global_load_dwordx2 v[162:163], v181, s[26:27] offset:3072 nt
	global_load_dwordx4 v[146:149], v166, s[24:25] offset:3072 nt
	global_load_dwordx2 v[164:165], v181, s[26:27] offset:3584 nt
	global_load_dwordx4 v[170:173], v166, s[34:35]
	s_waitcnt vmcnt(33)
	v_fmamk_f32 v183, v112, 0x3a000000, v182
	v_rsq_f32_e32 v183, v183
	v_lshlrev_b32_e32 v174, 16, v96
	v_and_b32_e32 v175, 0xffff0000, v96
	v_lshlrev_b32_e32 v176, 16, v97
	v_and_b32_e32 v177, 0xffff0000, v97
	v_mul_f32_e32 v174, v183, v174
	v_mul_f32_e32 v175, v183, v175
	v_mul_f32_e32 v176, v183, v176
	v_mul_f32_e32 v177, v183, v177
	v_fma_f32 v64, v0, v174, v64
	v_fma_f32 v65, v1, v175, v65
	v_fma_f32 v66, v2, v176, v66
	v_fma_f32 v67, v3, v177, v67
	global_store_dwordx4 v166, v[64:67], s[36:37] offset:-4096 nt
	v_mul_f32_e32 v185, v64, v64
	v_mul_f32_e32 v186, v65, v65
	v_mul_f32_e32 v187, v66, v66
	v_mul_f32_e32 v188, v67, v67
	s_waitcnt vmcnt(32)
; __device__ __forceinline__ unsigned pk2(float lo, float hi) { return pg8::cvt_pk_bf16(lo, hi); }
; __device__ __forceinline__ float bf_lo(unsigned w) { return __uint_as_float(w << 16); }
; __device__ __forceinline__ float bf_hi(unsigned w) { return __uint_as_float(w & 0xffff0000u); }
; __global__ void __launch_bounds__(512, 2) fwd(Params P) {
;     ...
;             for (int j = 0; j < 8; ++j) { const f32x4 xv = __builtin_nontemporal_load(&xr[64 * j]); const u32x2 yw = __builtin_nontemporal_load(&yr[64 * j]); const f32x4 g = g1[64 * j];
;                 f32x4 t; t.x = xv.x + bf_lo(yw.x) * rsy * g.x; t.y = xv.y + bf_hi(yw.x) * rsy * g.y; t.z = xv.z + bf_lo(yw.y) * rsy * g.z; t.w = xv.w + bf_hi(yw.y) * rsy * g.w;
;                 v[j] = t; __builtin_nontemporal_store(t, &orow[64 * j]); s += (t.x * t.x + t.y * t.y) + (t.z * t.z + t.w * t.w); }
;             const float rs = __builtin_amdgcn_rsqf(wave_sum(s) * (1.f / DM) + EPS);
;             u32x2* o = (u32x2*)(XN + (size_t)m * DM) + lane;
; #pragma unroll
;             for (int j = 0; j < 8; ++j) { const f32x4 g = g2[64 * j]; u32x2 w; w.x = pk2(v[j].x * rs * g.x, v[j].y * rs * g.y); w.y = pk2(v[j].z * rs * g.z, v[j].w * rs * g.w); o[64 * j] = w; }
	v_lshlrev_b32_e32 v174, 16, v98
	v_and_b32_e32 v175, 0xffff0000, v98
	v_lshlrev_b32_e32 v176, 16, v99
	v_and_b32_e32 v177, 0xffff0000, v99
	v_mul_f32_e32 v174, v183, v174
	v_mul_f32_e32 v175, v183, v175
	v_mul_f32_e32 v176, v183, v176
	v_mul_f32_e32 v177, v183, v177
	v_fma_f32 v68, v4, v174, v68
	v_fma_f32 v69, v5, v175, v69
	v_fma_f32 v70, v6, v176, v70
	v_fma_f32 v71, v7, v177, v71
	global_store_dwordx4 v166, v[68:71], s[36:37] offset:-3072 nt
	v_fma_f32 v185, v68, v68, v185
	v_fma_f32 v186, v69, v69, v186
	v_fma_f32 v187, v70, v70, v187
	v_fma_f32 v188, v71, v71, v188
	s_waitcnt vmcnt(31)
	v_lshlrev_b32_e32 v174, 16, v100
	v_and_b32_e32 v175, 0xffff0000, v100
	v_lshlrev_b32_e32 v176, 16, v101
	v_and_b32_e32 v177, 0xffff0000, v101
	v_mul_f32_e32 v174, v183, v174
	v_mul_f32_e32 v175, v183, v175
	v_mul_f32_e32 v176, v183, v176
	v_mul_f32_e32 v177, v183, v177
	v_fma_f32 v72, v8, v174, v72
	v_fma_f32 v73, v9, v175, v73
	v_fma_f32 v74, v10, v176, v74
	v_fma_f32 v75, v11, v177, v75
	global_store_dwordx4 v166, v[72:75], s[36:37] offset:-2048 nt
	v_fma_f32 v185, v72, v72, v185
	v_fma_f32 v186, v73, v73, v186
	v_fma_f32 v187, v74, v74, v187
	v_fma_f32 v188, v75, v75, v188
	s_waitcnt vmcnt(30)
	v_lshlrev_b32_e32 v174, 16, v102
	v_and_b32_e32 v175, 0xffff0000, v102
	v_lshlrev_b32_e32 v176, 16, v103
	v_and_b32_e32 v177, 0xffff0000, v103
	v_mul_f32_e32 v174, v183, v174
	v_mul_f32_e32 v175, v183, v175
	v_mul_f32_e32 v176, v183, v176
	v_mul_f32_e32 v177, v183, v177
	v_fma_f32 v76, v12, v174, v76
	v_fma_f32 v77, v13, v175, v77
	v_fma_f32 v78, v14, v176, v78
	v_fma_f32 v79, v15, v177, v79
	global_store_dwordx4 v166, v[76:79], s[36:37] offset:-1024 nt
	v_fma_f32 v185, v76, v76, v185
	v_fma_f32 v186, v77, v77, v186
	v_fma_f32 v187, v78, v78, v187
	v_fma_f32 v188, v79, v79, v188
	s_waitcnt vmcnt(29)
	v_lshlrev_b32_e32 v174, 16, v104
	v_and_b32_e32 v175, 0xffff0000, v104
	v_lshlrev_b32_e32 v176, 16, v105
	v_and_b32_e32 v177, 0xffff0000, v105
	v_mul_f32_e32 v174, v183, v174
	v_mul_f32_e32 v175, v183, v175
	v_mul_f32_e32 v176, v183, v176
	v_mul_f32_e32 v177, v183, v177
	v_fma_f32 v80, v16, v174, v80
	v_fma_f32 v81, v17, v175, v81
	v_fma_f32 v82, v18, v176, v82
	v_fma_f32 v83, v19, v177, v83
	global_store_dwordx4 v166, v[80:83], s[36:37] offset:0 nt
	v_fma_f32 v185, v80, v80, v185
	v_fma_f32 v186, v81, v81, v186
	v_fma_f32 v187, v82, v82, v187
	v_fma_f32 v188, v83, v83, v188
	s_waitcnt vmcnt(28)
	v_lshlrev_b32_e32 v174, 16, v106
	v_and_b32_e32 v175, 0xffff0000, v106
	v_lshlrev_b32_e32 v176, 16, v107
	v_and_b32_e32 v177, 0xffff0000, v107
	v_mul_f32_e32 v174, v183, v174
	v_mul_f32_e32 v175, v183, v175
	v_mul_f32_e32 v176, v183, v176
	v_mul_f32_e32 v177, v183, v177
	v_fma_f32 v84, v20, v174, v84
	v_fma_f32 v85, v21, v175, v85
	v_fma_f32 v86, v22, v176, v86
	v_fma_f32 v87, v23, v177, v87
	global_store_dwordx4 v166, v[84:87], s[36:37] offset:1024 nt
	v_fma_f32 v185, v84, v84, v185
	v_fma_f32 v186, v85, v85, v186
	v_fma_f32 v187, v86, v86, v187
	v_fma_f32 v188, v87, v87, v188
	s_waitcnt vmcnt(27)
	v_lshlrev_b32_e32 v174, 16, v108
	v_and_b32_e32 v175, 0xffff0000, v108
	v_lshlrev_b32_e32 v176, 16, v109
	v_and_b32_e32 v177, 0xffff0000, v109
	v_mul_f32_e32 v174, v183, v174
	v_mul_f32_e32 v175, v183, v175
	v_mul_f32_e32 v176, v183, v176
	v_mul_f32_e32 v177, v183, v177
	v_fma_f32 v88, v24, v174, v88
	v_fma_f32 v89, v25, v175, v89
	v_fma_f32 v90, v26, v176, v90
	v_fma_f32 v91, v27, v177, v91
	global_store_dwordx4 v166, v[88:91], s[36:37] offset:2048 nt
	v_fma_f32 v185, v88, v88, v185
	v_fma_f32 v186, v89, v89, v186
	v_fma_f32 v187, v90, v90, v187
	v_fma_f32 v188, v91, v91, v188
	s_waitcnt vmcnt(26)
	v_lshlrev_b32_e32 v174, 16, v110
	v_and_b32_e32 v175, 0xffff0000, v110
	v_lshlrev_b32_e32 v176, 16, v111
	v_and_b32_e32 v177, 0xffff0000, v111
	v_mul_f32_e32 v174, v183, v174
	v_mul_f32_e32 v175, v183, v175
	v_mul_f32_e32 v176, v183, v176
	v_mul_f32_e32 v177, v183, v177
	v_fma_f32 v92, v28, v174, v92
	v_fma_f32 v93, v29, v175, v93
	v_fma_f32 v94, v30, v176, v94
	v_fma_f32 v95, v31, v177, v95
	global_store_dwordx4 v166, v[92:95], s[36:37] offset:3072 nt
	v_fma_f32 v185, v92, v92, v185
	v_fma_f32 v186, v93, v93, v186
	v_fma_f32 v187, v94, v94, v187
	v_fma_f32 v188, v95, v95, v188
	v_add_f32_e32 v185, v185, v186
	v_add_f32_e32 v187, v187, v188
	v_add_f32_e32 v185, v185, v187
	s_nop 1
	v_add_f32_dpp v185, v185, v185 quad_perm:[1,0,3,2] row_mask:0xf bank_mask:0xf
	s_nop 1
	v_add_f32_dpp v185, v185, v185 quad_perm:[2,3,0,1] row_mask:0xf bank_mask:0xf
	s_nop 1
	v_add_f32_dpp v185, v185, v185 row_half_mirror row_mask:0xf bank_mask:0xf
	s_nop 1
	v_add_f32_dpp v185, v185, v185 row_mirror row_mask:0xf bank_mask:0xf
	s_nop 1
	v_readlane_b32 s24, v185, 0
	v_readlane_b32 s25, v185, 16
	v_readlane_b32 s26, v185, 32
	v_readlane_b32 s27, v185, 48
	v_mov_b32_e32 v184, s24
	v_add_f32_e32 v184, s25, v184
	v_add_f32_e32 v184, s26, v184
	v_add_f32_e32 v184, s27, v184
	v_fmamk_f32 v184, v184, 0x3a000000, v182
	v_rsq_f32_e32 v184, v184
	s_nop 0
	v_mul_f32_e32 v174, v184, v64
	v_mul_f32_e32 v175, v184, v65
	v_mul_f32_e32 v176, v184, v66
	v_mul_f32_e32 v177, v184, v67
	v_mul_f32_e32 v174, v174, v32
	v_mul_f32_e32 v175, v175, v33
	v_mul_f32_e32 v176, v176, v34
	v_mul_f32_e32 v177, v177, v35
	v_cvt_pk_bf16_f32 v96, v174, v175
	v_cvt_pk_bf16_f32 v97, v176, v177
	global_store_dwordx2 v181, v[96:97], s[38:39] offset:0
	v_mul_f32_e32 v174, v184, v68
	v_mul_f32_e32 v175, v184, v69
	v_mul_f32_e32 v176, v184, v70
	v_mul_f32_e32 v177, v184, v71
	v_mul_f32_e32 v174, v174, v36
	v_mul_f32_e32 v175, v175, v37
	v_mul_f32_e32 v176, v176, v38
	v_mul_f32_e32 v177, v177, v39
	v_cvt_pk_bf16_f32 v98, v174, v175
; __device__ __forceinline__ unsigned pk2(float lo, float hi) { return pg8::cvt_pk_bf16(lo, hi); }
; #define X_IN INP(0)
; #define P_IN INP(1)
; __global__ void __launch_bounds__(512, 2) fwd(Params P) {
;     ...
;         for (int m = gw; m < T_TOK; m += NGW) {
;             const float rsy = __builtin_amdgcn_rsqf(ssq_y[m] * (1.f / DM) + EPS);
;             const f32x4* xr = (const f32x4*)(X_IN + (size_t)m * DM) + lane; const u32x2* yr = (const u32x2*)(YB + (size_t)m * DM) + lane;
;             f32x4* orow = (f32x4*)(OUT_P + (size_t)m * DM) + lane;
;             f32x4 v[8]; float s = 0.f;
; #pragma unroll
;             for (int j = 0; j < 8; ++j) { const f32x4 xv = __builtin_nontemporal_load(&xr[64 * j]); const u32x2 yw = __builtin_nontemporal_load(&yr[64 * j]); const f32x4 g = g1[64 * j];
;     ...
;             for (int j = 0; j < 8; ++j) { const f32x4 g = g2[64 * j]; u32x2 w; w.x = pk2(v[j].x * rs * g.x, v[j].y * rs * g.y); w.y = pk2(v[j].z * rs * g.z, v[j].w * rs * g.w); o[64 * j] = w; }
;             const f32x4 pv = ((const f32x4*)(P_IN + (size_t)m * PLE))[lane]; u32x2 pw; pw.x = pk2(pv.x, pv.y); pw.y = pk2(pv.z, pv.w);
;             ((u32x2*)(PB + (size_t)m * PLE))[lane] = pw;
	v_cvt_pk_bf16_f32 v99, v176, v177
	global_store_dwordx2 v181, v[98:99], s[38:39] offset:512
	v_mul_f32_e32 v174, v184, v72
	v_mul_f32_e32 v175, v184, v73
	v_mul_f32_e32 v176, v184, v74
	v_mul_f32_e32 v177, v184, v75
	v_mul_f32_e32 v174, v174, v40
	v_mul_f32_e32 v175, v175, v41
	v_mul_f32_e32 v176, v176, v42
	v_mul_f32_e32 v177, v177, v43
	v_cvt_pk_bf16_f32 v100, v174, v175
	v_cvt_pk_bf16_f32 v101, v176, v177
	global_store_dwordx2 v181, v[100:101], s[38:39] offset:1024
	v_mul_f32_e32 v174, v184, v76
	v_mul_f32_e32 v175, v184, v77
	v_mul_f32_e32 v176, v184, v78
	v_mul_f32_e32 v177, v184, v79
	v_mul_f32_e32 v174, v174, v44
	v_mul_f32_e32 v175, v175, v45
	v_mul_f32_e32 v176, v176, v46
	v_mul_f32_e32 v177, v177, v47
	v_cvt_pk_bf16_f32 v102, v174, v175
	v_cvt_pk_bf16_f32 v103, v176, v177
	global_store_dwordx2 v181, v[102:103], s[38:39] offset:1536
	v_mul_f32_e32 v174, v184, v80
	v_mul_f32_e32 v175, v184, v81
	v_mul_f32_e32 v176, v184, v82
	v_mul_f32_e32 v177, v184, v83
	v_mul_f32_e32 v174, v174, v48
	v_mul_f32_e32 v175, v175, v49
	v_mul_f32_e32 v176, v176, v50
	v_mul_f32_e32 v177, v177, v51
	v_cvt_pk_bf16_f32 v104, v174, v175
	v_cvt_pk_bf16_f32 v105, v176, v177
	global_store_dwordx2 v181, v[104:105], s[38:39] offset:2048
	v_mul_f32_e32 v174, v184, v84
	v_mul_f32_e32 v175, v184, v85
	v_mul_f32_e32 v176, v184, v86
	v_mul_f32_e32 v177, v184, v87
	v_mul_f32_e32 v174, v174, v52
	v_mul_f32_e32 v175, v175, v53
	v_mul_f32_e32 v176, v176, v54
	v_mul_f32_e32 v177, v177, v55
	v_cvt_pk_bf16_f32 v106, v174, v175
	v_cvt_pk_bf16_f32 v107, v176, v177
	global_store_dwordx2 v181, v[106:107], s[38:39] offset:2560
	v_mul_f32_e32 v174, v184, v88
	v_mul_f32_e32 v175, v184, v89
	v_mul_f32_e32 v176, v184, v90
	v_mul_f32_e32 v177, v184, v91
	v_mul_f32_e32 v174, v174, v56
	v_mul_f32_e32 v175, v175, v57
	v_mul_f32_e32 v176, v176, v58
	v_mul_f32_e32 v177, v177, v59
	v_cvt_pk_bf16_f32 v108, v174, v175
	v_cvt_pk_bf16_f32 v109, v176, v177
	global_store_dwordx2 v181, v[108:109], s[38:39] offset:3072
	v_mul_f32_e32 v174, v184, v92
	v_mul_f32_e32 v175, v184, v93
	v_mul_f32_e32 v176, v184, v94
	v_mul_f32_e32 v177, v184, v95
	v_mul_f32_e32 v174, v174, v60
	v_mul_f32_e32 v175, v175, v61
	v_mul_f32_e32 v176, v176, v62
	v_mul_f32_e32 v177, v177, v63
	v_cvt_pk_bf16_f32 v110, v174, v175
	v_cvt_pk_bf16_f32 v111, v176, v177
	global_store_dwordx2 v181, v[110:111], s[38:39] offset:3584
	s_waitcnt vmcnt(34)
	v_cvt_pk_bf16_f32 v114, v114, v115
	v_cvt_pk_bf16_f32 v115, v116, v117
	global_store_dwordx2 v181, v[114:115], s[40:41]
	s_add_i32 s30, s30, s82
	s_cmpk_gt_i32 s30, 0x7fff
	s_cbranch_scc1 .Lp5b_done
.Lp5b_loop:
	s_lshl_b32 s2, s30, 13
	s_add_u32 s36, s18, s2
	s_addc_u32 s37, s19, 0
	s_lshl_b32 s2, s30, 12
	s_add_u32 s38, s16, s2
	s_addc_u32 s39, s17, 0
	s_lshl_b32 s2, s30, 9
	s_add_u32 s40, s22, s2
	s_addc_u32 s41, s23, 0
	s_add_i32 s10, s30, s82
	s_cmpk_gt_i32 s10, 0x7fff
	s_cselect_b32 s10, s30, s10
	s_lshl_b32 s2, s10, 13
	s_add_u32 s24, s8, s2
	s_addc_u32 s25, s9, 0
	s_lshl_b32 s2, s10, 12
	s_add_u32 s26, s14, s2
	s_addc_u32 s27, s15, 0
	s_lshl_b32 s2, s10, 2
	s_add_u32 s28, s12, s2
	s_addc_u32 s29, s13, 0
	s_lshl_b32 s2, s10, 10
	s_add_u32 s34, s20, s2
	s_addc_u32 s35, s21, 0
	global_load_dword v112, v167, s[28:29]
	global_load_dwordx4 v[64:67], v166, s[24:25] offset:-4096 nt
	global_load_dwordx2 v[96:97], v181, s[26:27] offset:0 nt
	global_load_dwordx4 v[68:71], v166, s[24:25] offset:-3072 nt
	global_load_dwordx2 v[98:99], v181, s[26:27] offset:512 nt
	global_load_dwordx4 v[72:75], v166, s[24:25] offset:-2048 nt
	global_load_dwordx2 v[100:101], v181, s[26:27] offset:1024 nt
	global_load_dwordx4 v[76:79], v166, s[24:25] offset:-1024 nt
	global_load_dwordx2 v[102:103], v181, s[26:27] offset:1536 nt
	global_load_dwordx4 v[80:83], v166, s[24:25] offset:0 nt
	global_load_dwordx2 v[104:105], v181, s[26:27] offset:2048 nt
	global_load_dwordx4 v[84:87], v166, s[24:25] offset:1024 nt
	global_load_dwordx2 v[106:107], v181, s[26:27] offset:2560 nt
	global_load_dwordx4 v[88:91], v166, s[24:25] offset:2048 nt
	global_load_dwordx2 v[108:109], v181, s[26:27] offset:3072 nt
	global_load_dwordx4 v[92:95], v166, s[24:25] offset:3072 nt
	global_load_dwordx2 v[110:111], v181, s[26:27] offset:3584 nt
	global_load_dwordx4 v[114:117], v166, s[34:35]
	s_waitcnt vmcnt(50)
	v_fmamk_f32 v183, v168, 0x3a000000, v182
	v_rsq_f32_e32 v183, v183
	v_lshlrev_b32_e32 v174, 16, v150
	v_and_b32_e32 v175, 0xffff0000, v150
	v_lshlrev_b32_e32 v176, 16, v151
	v_and_b32_e32 v177, 0xffff0000, v151
	v_mul_f32_e32 v174, v183, v174
	v_mul_f32_e32 v175, v183, v175
	v_mul_f32_e32 v176, v183, v176
	v_mul_f32_e32 v177, v183, v177
	v_fma_f32 v118, v0, v174, v118
	v_fma_f32 v119, v1, v175, v119
	v_fma_f32 v120, v2, v176, v120
	v_fma_f32 v121, v3, v177, v121
	global_store_dwordx4 v166, v[118:121], s[36:37] offset:-4096 nt
	v_mul_f32_e32 v185, v118, v118
	v_mul_f32_e32 v186, v119, v119
	v_mul_f32_e32 v187, v120, v120
	v_mul_f32_e32 v188, v121, v121
	s_waitcnt vmcnt(49)
	v_lshlrev_b32_e32 v174, 16, v152
	v_and_b32_e32 v175, 0xffff0000, v152
	v_lshlrev_b32_e32 v176, 16, v153
	v_and_b32_e32 v177, 0xffff0000, v153
	v_mul_f32_e32 v174, v183, v174
	v_mul_f32_e32 v175, v183, v175
	v_mul_f32_e32 v176, v183, v176
	v_mul_f32_e32 v177, v183, v177
	v_fma_f32 v122, v4, v174, v122
	v_fma_f32 v123, v5, v175, v123
	v_fma_f32 v124, v6, v176, v124
	v_fma_f32 v125, v7, v177, v125
	global_store_dwordx4 v166, v[122:125], s[36:37] offset:-3072 nt
	v_fma_f32 v185, v122, v122, v185
	v_fma_f32 v186, v123, v123, v186
	v_fma_f32 v187, v124, v124, v187
	v_fma_f32 v188, v125, v125, v188
	s_waitcnt vmcnt(48)
; __device__ __forceinline__ unsigned pk2(float lo, float hi) { return pg8::cvt_pk_bf16(lo, hi); }
; __device__ __forceinline__ float bf_lo(unsigned w) { return __uint_as_float(w << 16); }
; __device__ __forceinline__ float bf_hi(unsigned w) { return __uint_as_float(w & 0xffff0000u); }
; __global__ void __launch_bounds__(512, 2) fwd(Params P) {
;     ...
;             for (int j = 0; j < 8; ++j) { const f32x4 xv = __builtin_nontemporal_load(&xr[64 * j]); const u32x2 yw = __builtin_nontemporal_load(&yr[64 * j]); const f32x4 g = g1[64 * j];
;                 f32x4 t; t.x = xv.x + bf_lo(yw.x) * rsy * g.x; t.y = xv.y + bf_hi(yw.x) * rsy * g.y; t.z = xv.z + bf_lo(yw.y) * rsy * g.z; t.w = xv.w + bf_hi(yw.y) * rsy * g.w;
;                 v[j] = t; __builtin_nontemporal_store(t, &orow[64 * j]); s += (t.x * t.x + t.y * t.y) + (t.z * t.z + t.w * t.w); }
;             const float rs = __builtin_amdgcn_rsqf(wave_sum(s) * (1.f / DM) + EPS);
;             u32x2* o = (u32x2*)(XN + (size_t)m * DM) + lane;
; #pragma unroll
;             for (int j = 0; j < 8; ++j) { const f32x4 g = g2[64 * j]; u32x2 w; w.x = pk2(v[j].x * rs * g.x, v[j].y * rs * g.y); w.y = pk2(v[j].z * rs * g.z, v[j].w * rs * g.w); o[64 * j] = w; }
	v_lshlrev_b32_e32 v174, 16, v154
	v_and_b32_e32 v175, 0xffff0000, v154
	v_lshlrev_b32_e32 v176, 16, v155
	v_and_b32_e32 v177, 0xffff0000, v155
	v_mul_f32_e32 v174, v183, v174
	v_mul_f32_e32 v175, v183, v175
	v_mul_f32_e32 v176, v183, v176
	v_mul_f32_e32 v177, v183, v177
	v_fma_f32 v126, v8, v174, v126
	v_fma_f32 v127, v9, v175, v127
	v_fma_f32 v128, v10, v176, v128
	v_fma_f32 v129, v11, v177, v129
	global_store_dwordx4 v166, v[126:129], s[36:37] offset:-2048 nt
	v_fma_f32 v185, v126, v126, v185
	v_fma_f32 v186, v127, v127, v186
	v_fma_f32 v187, v128, v128, v187
	v_fma_f32 v188, v129, v129, v188
	s_waitcnt vmcnt(47)
	v_lshlrev_b32_e32 v174, 16, v156
	v_and_b32_e32 v175, 0xffff0000, v156
	v_lshlrev_b32_e32 v176, 16, v157
	v_and_b32_e32 v177, 0xffff0000, v157
	v_mul_f32_e32 v174, v183, v174
	v_mul_f32_e32 v175, v183, v175
	v_mul_f32_e32 v176, v183, v176
	v_mul_f32_e32 v177, v183, v177
	v_fma_f32 v130, v12, v174, v130
	v_fma_f32 v131, v13, v175, v131
	v_fma_f32 v132, v14, v176, v132
	v_fma_f32 v133, v15, v177, v133
	global_store_dwordx4 v166, v[130:133], s[36:37] offset:-1024 nt
	v_fma_f32 v185, v130, v130, v185
	v_fma_f32 v186, v131, v131, v186
	v_fma_f32 v187, v132, v132, v187
	v_fma_f32 v188, v133, v133, v188
	s_waitcnt vmcnt(46)
	v_lshlrev_b32_e32 v174, 16, v158
	v_and_b32_e32 v175, 0xffff0000, v158
	v_lshlrev_b32_e32 v176, 16, v159
	v_and_b32_e32 v177, 0xffff0000, v159
	v_mul_f32_e32 v174, v183, v174
	v_mul_f32_e32 v175, v183, v175
	v_mul_f32_e32 v176, v183, v176
	v_mul_f32_e32 v177, v183, v177
	v_fma_f32 v134, v16, v174, v134
	v_fma_f32 v135, v17, v175, v135
	v_fma_f32 v136, v18, v176, v136
	v_fma_f32 v137, v19, v177, v137
	global_store_dwordx4 v166, v[134:137], s[36:37] offset:0 nt
	v_fma_f32 v185, v134, v134, v185
	v_fma_f32 v186, v135, v135, v186
	v_fma_f32 v187, v136, v136, v187
	v_fma_f32 v188, v137, v137, v188
	s_waitcnt vmcnt(45)
	v_lshlrev_b32_e32 v174, 16, v160
	v_and_b32_e32 v175, 0xffff0000, v160
	v_lshlrev_b32_e32 v176, 16, v161
	v_and_b32_e32 v177, 0xffff0000, v161
	v_mul_f32_e32 v174, v183, v174
	v_mul_f32_e32 v175, v183, v175
	v_mul_f32_e32 v176, v183, v176
	v_mul_f32_e32 v177, v183, v177
	v_fma_f32 v138, v20, v174, v138
	v_fma_f32 v139, v21, v175, v139
	v_fma_f32 v140, v22, v176, v140
	v_fma_f32 v141, v23, v177, v141
	global_store_dwordx4 v166, v[138:141], s[36:37] offset:1024 nt
	v_fma_f32 v185, v138, v138, v185
	v_fma_f32 v186, v139, v139, v186
	v_fma_f32 v187, v140, v140, v187
	v_fma_f32 v188, v141, v141, v188
	s_waitcnt vmcnt(44)
	v_lshlrev_b32_e32 v174, 16, v162
	v_and_b32_e32 v175, 0xffff0000, v162
	v_lshlrev_b32_e32 v176, 16, v163
	v_and_b32_e32 v177, 0xffff0000, v163
	v_mul_f32_e32 v174, v183, v174
	v_mul_f32_e32 v175, v183, v175
	v_mul_f32_e32 v176, v183, v176
	v_mul_f32_e32 v177, v183, v177
	v_fma_f32 v142, v24, v174, v142
	v_fma_f32 v143, v25, v175, v143
	v_fma_f32 v144, v26, v176, v144
	v_fma_f32 v145, v27, v177, v145
	global_store_dwordx4 v166, v[142:145], s[36:37] offset:2048 nt
	v_fma_f32 v185, v142, v142, v185
	v_fma_f32 v186, v143, v143, v186
	v_fma_f32 v187, v144, v144, v187
	v_fma_f32 v188, v145, v145, v188
	s_waitcnt vmcnt(43)
	v_lshlrev_b32_e32 v174, 16, v164
	v_and_b32_e32 v175, 0xffff0000, v164
	v_lshlrev_b32_e32 v176, 16, v165
	v_and_b32_e32 v177, 0xffff0000, v165
	v_mul_f32_e32 v174, v183, v174
	v_mul_f32_e32 v175, v183, v175
	v_mul_f32_e32 v176, v183, v176
	v_mul_f32_e32 v177, v183, v177
	v_fma_f32 v146, v28, v174, v146
	v_fma_f32 v147, v29, v175, v147
	v_fma_f32 v148, v30, v176, v148
	v_fma_f32 v149, v31, v177, v149
	global_store_dwordx4 v166, v[146:149], s[36:37] offset:3072 nt
	v_fma_f32 v185, v146, v146, v185
	v_fma_f32 v186, v147, v147, v186
	v_fma_f32 v187, v148, v148, v187
	v_fma_f32 v188, v149, v149, v188
	v_add_f32_e32 v185, v185, v186
	v_add_f32_e32 v187, v187, v188
	v_add_f32_e32 v185, v185, v187
	s_nop 1
	v_add_f32_dpp v185, v185, v185 quad_perm:[1,0,3,2] row_mask:0xf bank_mask:0xf
	s_nop 1
	v_add_f32_dpp v185, v185, v185 quad_perm:[2,3,0,1] row_mask:0xf bank_mask:0xf
	s_nop 1
	v_add_f32_dpp v185, v185, v185 row_half_mirror row_mask:0xf bank_mask:0xf
	s_nop 1
	v_add_f32_dpp v185, v185, v185 row_mirror row_mask:0xf bank_mask:0xf
	s_nop 1
	v_readlane_b32 s24, v185, 0
	v_readlane_b32 s25, v185, 16
	v_readlane_b32 s26, v185, 32
	v_readlane_b32 s27, v185, 48
	v_mov_b32_e32 v184, s24
	v_add_f32_e32 v184, s25, v184
	v_add_f32_e32 v184, s26, v184
	v_add_f32_e32 v184, s27, v184
	v_fmamk_f32 v184, v184, 0x3a000000, v182
	v_rsq_f32_e32 v184, v184
	s_nop 0
	v_mul_f32_e32 v174, v184, v118
	v_mul_f32_e32 v175, v184, v119
	v_mul_f32_e32 v176, v184, v120
	v_mul_f32_e32 v177, v184, v121
	v_mul_f32_e32 v174, v174, v32
	v_mul_f32_e32 v175, v175, v33
	v_mul_f32_e32 v176, v176, v34
	v_mul_f32_e32 v177, v177, v35
	v_cvt_pk_bf16_f32 v150, v174, v175
	v_cvt_pk_bf16_f32 v151, v176, v177
	global_store_dwordx2 v181, v[150:151], s[38:39] offset:0
	v_mul_f32_e32 v174, v184, v122
	v_mul_f32_e32 v175, v184, v123
	v_mul_f32_e32 v176, v184, v124
	v_mul_f32_e32 v177, v184, v125
	v_mul_f32_e32 v174, v174, v36
	v_mul_f32_e32 v175, v175, v37
	v_mul_f32_e32 v176, v176, v38
	v_mul_f32_e32 v177, v177, v39
	v_cvt_pk_bf16_f32 v152, v174, v175
	v_cvt_pk_bf16_f32 v153, v176, v177
	global_store_dwordx2 v181, v[152:153], s[38:39] offset:512
	v_mul_f32_e32 v174, v184, v126
	v_mul_f32_e32 v175, v184, v127
	v_mul_f32_e32 v176, v184, v128
	v_mul_f32_e32 v177, v184, v129
	v_mul_f32_e32 v174, v174, v40
	v_mul_f32_e32 v175, v175, v41
	v_mul_f32_e32 v176, v176, v42
	v_mul_f32_e32 v177, v177, v43
	v_cvt_pk_bf16_f32 v154, v174, v175
	v_cvt_pk_bf16_f32 v155, v176, v177
	global_store_dwordx2 v181, v[154:155], s[38:39] offset:1024
; __device__ __forceinline__ unsigned pk2(float lo, float hi) { return pg8::cvt_pk_bf16(lo, hi); }
; __device__ __forceinline__ float bf_lo(unsigned w) { return __uint_as_float(w << 16); }
; __device__ __forceinline__ float bf_hi(unsigned w) { return __uint_as_float(w & 0xffff0000u); }
; #define X_IN INP(0)
; #define P_IN INP(1)
; __global__ void __launch_bounds__(512, 2) fwd(Params P) {
;     ...
;         for (int m = gw; m < T_TOK; m += NGW) {
;             const float rsy = __builtin_amdgcn_rsqf(ssq_y[m] * (1.f / DM) + EPS);
;             const f32x4* xr = (const f32x4*)(X_IN + (size_t)m * DM) + lane; const u32x2* yr = (const u32x2*)(YB + (size_t)m * DM) + lane;
;             f32x4* orow = (f32x4*)(OUT_P + (size_t)m * DM) + lane;
;             f32x4 v[8]; float s = 0.f;
; #pragma unroll
;             for (int j = 0; j < 8; ++j) { const f32x4 xv = __builtin_nontemporal_load(&xr[64 * j]); const u32x2 yw = __builtin_nontemporal_load(&yr[64 * j]); const f32x4 g = g1[64 * j];
;                 f32x4 t; t.x = xv.x + bf_lo(yw.x) * rsy * g.x; t.y = xv.y + bf_hi(yw.x) * rsy * g.y; t.z = xv.z + bf_lo(yw.y) * rsy * g.z; t.w = xv.w + bf_hi(yw.y) * rsy * g.w;
;                 v[j] = t; __builtin_nontemporal_store(t, &orow[64 * j]); s += (t.x * t.x + t.y * t.y) + (t.z * t.z + t.w * t.w); }
;     ...
; #pragma unroll
;             for (int j = 0; j < 8; ++j) { const f32x4 g = g2[64 * j]; u32x2 w; w.x = pk2(v[j].x * rs * g.x, v[j].y * rs * g.y); w.y = pk2(v[j].z * rs * g.z, v[j].w * rs * g.w); o[64 * j] = w; }
;             const f32x4 pv = ((const f32x4*)(P_IN + (size_t)m * PLE))[lane]; u32x2 pw; pw.x = pk2(pv.x, pv.y); pw.y = pk2(pv.z, pv.w);
;             ((u32x2*)(PB + (size_t)m * PLE))[lane] = pw;
	v_mul_f32_e32 v174, v184, v130
	v_mul_f32_e32 v175, v184, v131
	v_mul_f32_e32 v176, v184, v132
	v_mul_f32_e32 v177, v184, v133
	v_mul_f32_e32 v174, v174, v44
	v_mul_f32_e32 v175, v175, v45
	v_mul_f32_e32 v176, v176, v46
	v_mul_f32_e32 v177, v177, v47
	v_cvt_pk_bf16_f32 v156, v174, v175
	v_cvt_pk_bf16_f32 v157, v176, v177
	global_store_dwordx2 v181, v[156:157], s[38:39] offset:1536
	v_mul_f32_e32 v174, v184, v134
	v_mul_f32_e32 v175, v184, v135
	v_mul_f32_e32 v176, v184, v136
	v_mul_f32_e32 v177, v184, v137
	v_mul_f32_e32 v174, v174, v48
	v_mul_f32_e32 v175, v175, v49
	v_mul_f32_e32 v176, v176, v50
	v_mul_f32_e32 v177, v177, v51
	v_cvt_pk_bf16_f32 v158, v174, v175
	v_cvt_pk_bf16_f32 v159, v176, v177
	global_store_dwordx2 v181, v[158:159], s[38:39] offset:2048
	v_mul_f32_e32 v174, v184, v138
	v_mul_f32_e32 v175, v184, v139
	v_mul_f32_e32 v176, v184, v140
	v_mul_f32_e32 v177, v184, v141
	v_mul_f32_e32 v174, v174, v52
	v_mul_f32_e32 v175, v175, v53
	v_mul_f32_e32 v176, v176, v54
	v_mul_f32_e32 v177, v177, v55
	v_cvt_pk_bf16_f32 v160, v174, v175
	v_cvt_pk_bf16_f32 v161, v176, v177
	global_store_dwordx2 v181, v[160:161], s[38:39] offset:2560
	v_mul_f32_e32 v174, v184, v142
	v_mul_f32_e32 v175, v184, v143
	v_mul_f32_e32 v176, v184, v144
	v_mul_f32_e32 v177, v184, v145
	v_mul_f32_e32 v174, v174, v56
	v_mul_f32_e32 v175, v175, v57
	v_mul_f32_e32 v176, v176, v58
	v_mul_f32_e32 v177, v177, v59
	v_cvt_pk_bf16_f32 v162, v174, v175
	v_cvt_pk_bf16_f32 v163, v176, v177
	global_store_dwordx2 v181, v[162:163], s[38:39] offset:3072
	v_mul_f32_e32 v174, v184, v146
	v_mul_f32_e32 v175, v184, v147
	v_mul_f32_e32 v176, v184, v148
	v_mul_f32_e32 v177, v184, v149
	v_mul_f32_e32 v174, v174, v60
	v_mul_f32_e32 v175, v175, v61
	v_mul_f32_e32 v176, v176, v62
	v_mul_f32_e32 v177, v177, v63
	v_cvt_pk_bf16_f32 v164, v174, v175
	v_cvt_pk_bf16_f32 v165, v176, v177
	global_store_dwordx2 v181, v[164:165], s[38:39] offset:3584
	s_waitcnt vmcnt(51)
	v_cvt_pk_bf16_f32 v170, v170, v171
	v_cvt_pk_bf16_f32 v171, v172, v173
	global_store_dwordx2 v181, v[170:171], s[40:41]
	s_add_i32 s30, s30, s82
	s_cmpk_gt_i32 s30, 0x7fff
	s_cbranch_scc1 .Lp5b_done
	s_lshl_b32 s2, s30, 13
	s_add_u32 s36, s18, s2
	s_addc_u32 s37, s19, 0
	s_lshl_b32 s2, s30, 12
	s_add_u32 s38, s16, s2
	s_addc_u32 s39, s17, 0
	s_lshl_b32 s2, s30, 9
	s_add_u32 s40, s22, s2
	s_addc_u32 s41, s23, 0
	s_add_i32 s10, s30, s82
	s_cmpk_gt_i32 s10, 0x7fff
	s_cselect_b32 s10, s30, s10
	s_lshl_b32 s2, s10, 13
	s_add_u32 s24, s8, s2
	s_addc_u32 s25, s9, 0
	s_lshl_b32 s2, s10, 12
	s_add_u32 s26, s14, s2
	s_addc_u32 s27, s15, 0
	s_lshl_b32 s2, s10, 2
	s_add_u32 s28, s12, s2
	s_addc_u32 s29, s13, 0
	s_lshl_b32 s2, s10, 10
	s_add_u32 s34, s20, s2
	s_addc_u32 s35, s21, 0
	global_load_dword v168, v167, s[28:29]
	global_load_dwordx4 v[118:121], v166, s[24:25] offset:-4096 nt
	global_load_dwordx2 v[150:151], v181, s[26:27] offset:0 nt
	global_load_dwordx4 v[122:125], v166, s[24:25] offset:-3072 nt
	global_load_dwordx2 v[152:153], v181, s[26:27] offset:512 nt
	global_load_dwordx4 v[126:129], v166, s[24:25] offset:-2048 nt
	global_load_dwordx2 v[154:155], v181, s[26:27] offset:1024 nt
	global_load_dwordx4 v[130:133], v166, s[24:25] offset:-1024 nt
	global_load_dwordx2 v[156:157], v181, s[26:27] offset:1536 nt
	global_load_dwordx4 v[134:137], v166, s[24:25] offset:0 nt
	global_load_dwordx2 v[158:159], v181, s[26:27] offset:2048 nt
	global_load_dwordx4 v[138:141], v166, s[24:25] offset:1024 nt
	global_load_dwordx2 v[160:161], v181, s[26:27] offset:2560 nt
	global_load_dwordx4 v[142:145], v166, s[24:25] offset:2048 nt
	global_load_dwordx2 v[162:163], v181, s[26:27] offset:3072 nt
	global_load_dwordx4 v[146:149], v166, s[24:25] offset:3072 nt
	global_load_dwordx2 v[164:165], v181, s[26:27] offset:3584 nt
	global_load_dwordx4 v[170:173], v166, s[34:35]
	s_waitcnt vmcnt(50)
	v_fmamk_f32 v183, v112, 0x3a000000, v182
	v_rsq_f32_e32 v183, v183
	v_lshlrev_b32_e32 v174, 16, v96
	v_and_b32_e32 v175, 0xffff0000, v96
	v_lshlrev_b32_e32 v176, 16, v97
	v_and_b32_e32 v177, 0xffff0000, v97
	v_mul_f32_e32 v174, v183, v174
	v_mul_f32_e32 v175, v183, v175
	v_mul_f32_e32 v176, v183, v176
	v_mul_f32_e32 v177, v183, v177
	v_fma_f32 v64, v0, v174, v64
	v_fma_f32 v65, v1, v175, v65
	v_fma_f32 v66, v2, v176, v66
	v_fma_f32 v67, v3, v177, v67
	global_store_dwordx4 v166, v[64:67], s[36:37] offset:-4096 nt
	v_mul_f32_e32 v185, v64, v64
	v_mul_f32_e32 v186, v65, v65
	v_mul_f32_e32 v187, v66, v66
	v_mul_f32_e32 v188, v67, v67
	s_waitcnt vmcnt(49)
	v_lshlrev_b32_e32 v174, 16, v98
	v_and_b32_e32 v175, 0xffff0000, v98
	v_lshlrev_b32_e32 v176, 16, v99
	v_and_b32_e32 v177, 0xffff0000, v99
	v_mul_f32_e32 v174, v183, v174
	v_mul_f32_e32 v175, v183, v175
	v_mul_f32_e32 v176, v183, v176
	v_mul_f32_e32 v177, v183, v177
	v_fma_f32 v68, v4, v174, v68
	v_fma_f32 v69, v5, v175, v69
	v_fma_f32 v70, v6, v176, v70
	v_fma_f32 v71, v7, v177, v71
	global_store_dwordx4 v166, v[68:71], s[36:37] offset:-3072 nt
	v_fma_f32 v185, v68, v68, v185
	v_fma_f32 v186, v69, v69, v186
	v_fma_f32 v187, v70, v70, v187
	v_fma_f32 v188, v71, v71, v188
	s_waitcnt vmcnt(48)
	v_lshlrev_b32_e32 v174, 16, v100
	v_and_b32_e32 v175, 0xffff0000, v100
	v_lshlrev_b32_e32 v176, 16, v101
	v_and_b32_e32 v177, 0xffff0000, v101
	v_mul_f32_e32 v174, v183, v174
	v_mul_f32_e32 v175, v183, v175
	v_mul_f32_e32 v176, v183, v176
	v_mul_f32_e32 v177, v183, v177
	v_fma_f32 v72, v8, v174, v72
	v_fma_f32 v73, v9, v175, v73
	v_fma_f32 v74, v10, v176, v74
	v_fma_f32 v75, v11, v177, v75
	global_store_dwordx4 v166, v[72:75], s[36:37] offset:-2048 nt
	v_fma_f32 v185, v72, v72, v185
	v_fma_f32 v186, v73, v73, v186
	v_fma_f32 v187, v74, v74, v187
	v_fma_f32 v188, v75, v75, v188
	s_waitcnt vmcnt(47)
; __device__ __forceinline__ unsigned pk2(float lo, float hi) { return pg8::cvt_pk_bf16(lo, hi); }
; __device__ __forceinline__ float bf_lo(unsigned w) { return __uint_as_float(w << 16); }
; __device__ __forceinline__ float bf_hi(unsigned w) { return __uint_as_float(w & 0xffff0000u); }
; __global__ void __launch_bounds__(512, 2) fwd(Params P) {
;     ...
;             for (int j = 0; j < 8; ++j) { const f32x4 xv = __builtin_nontemporal_load(&xr[64 * j]); const u32x2 yw = __builtin_nontemporal_load(&yr[64 * j]); const f32x4 g = g1[64 * j];
;                 f32x4 t; t.x = xv.x + bf_lo(yw.x) * rsy * g.x; t.y = xv.y + bf_hi(yw.x) * rsy * g.y; t.z = xv.z + bf_lo(yw.y) * rsy * g.z; t.w = xv.w + bf_hi(yw.y) * rsy * g.w;
;                 v[j] = t; __builtin_nontemporal_store(t, &orow[64 * j]); s += (t.x * t.x + t.y * t.y) + (t.z * t.z + t.w * t.w); }
;             const float rs = __builtin_amdgcn_rsqf(wave_sum(s) * (1.f / DM) + EPS);
;             u32x2* o = (u32x2*)(XN + (size_t)m * DM) + lane;
; #pragma unroll
;             for (int j = 0; j < 8; ++j) { const f32x4 g = g2[64 * j]; u32x2 w; w.x = pk2(v[j].x * rs * g.x, v[j].y * rs * g.y); w.y = pk2(v[j].z * rs * g.z, v[j].w * rs * g.w); o[64 * j] = w; }
	v_lshlrev_b32_e32 v174, 16, v102
	v_and_b32_e32 v175, 0xffff0000, v102
	v_lshlrev_b32_e32 v176, 16, v103
	v_and_b32_e32 v177, 0xffff0000, v103
	v_mul_f32_e32 v174, v183, v174
	v_mul_f32_e32 v175, v183, v175
	v_mul_f32_e32 v176, v183, v176
	v_mul_f32_e32 v177, v183, v177
	v_fma_f32 v76, v12, v174, v76
	v_fma_f32 v77, v13, v175, v77
	v_fma_f32 v78, v14, v176, v78
	v_fma_f32 v79, v15, v177, v79
	global_store_dwordx4 v166, v[76:79], s[36:37] offset:-1024 nt
	v_fma_f32 v185, v76, v76, v185
	v_fma_f32 v186, v77, v77, v186
	v_fma_f32 v187, v78, v78, v187
	v_fma_f32 v188, v79, v79, v188
	s_waitcnt vmcnt(46)
	v_lshlrev_b32_e32 v174, 16, v104
	v_and_b32_e32 v175, 0xffff0000, v104
	v_lshlrev_b32_e32 v176, 16, v105
	v_and_b32_e32 v177, 0xffff0000, v105
	v_mul_f32_e32 v174, v183, v174
	v_mul_f32_e32 v175, v183, v175
	v_mul_f32_e32 v176, v183, v176
	v_mul_f32_e32 v177, v183, v177
	v_fma_f32 v80, v16, v174, v80
	v_fma_f32 v81, v17, v175, v81
	v_fma_f32 v82, v18, v176, v82
	v_fma_f32 v83, v19, v177, v83
	global_store_dwordx4 v166, v[80:83], s[36:37] offset:0 nt
	v_fma_f32 v185, v80, v80, v185
	v_fma_f32 v186, v81, v81, v186
	v_fma_f32 v187, v82, v82, v187
	v_fma_f32 v188, v83, v83, v188
	s_waitcnt vmcnt(45)
	v_lshlrev_b32_e32 v174, 16, v106
	v_and_b32_e32 v175, 0xffff0000, v106
	v_lshlrev_b32_e32 v176, 16, v107
	v_and_b32_e32 v177, 0xffff0000, v107
	v_mul_f32_e32 v174, v183, v174
	v_mul_f32_e32 v175, v183, v175
	v_mul_f32_e32 v176, v183, v176
	v_mul_f32_e32 v177, v183, v177
	v_fma_f32 v84, v20, v174, v84
	v_fma_f32 v85, v21, v175, v85
	v_fma_f32 v86, v22, v176, v86
	v_fma_f32 v87, v23, v177, v87
	global_store_dwordx4 v166, v[84:87], s[36:37] offset:1024 nt
	v_fma_f32 v185, v84, v84, v185
	v_fma_f32 v186, v85, v85, v186
	v_fma_f32 v187, v86, v86, v187
	v_fma_f32 v188, v87, v87, v188
	s_waitcnt vmcnt(44)
	v_lshlrev_b32_e32 v174, 16, v108
	v_and_b32_e32 v175, 0xffff0000, v108
	v_lshlrev_b32_e32 v176, 16, v109
	v_and_b32_e32 v177, 0xffff0000, v109
	v_mul_f32_e32 v174, v183, v174
	v_mul_f32_e32 v175, v183, v175
	v_mul_f32_e32 v176, v183, v176
	v_mul_f32_e32 v177, v183, v177
	v_fma_f32 v88, v24, v174, v88
	v_fma_f32 v89, v25, v175, v89
	v_fma_f32 v90, v26, v176, v90
	v_fma_f32 v91, v27, v177, v91
	global_store_dwordx4 v166, v[88:91], s[36:37] offset:2048 nt
	v_fma_f32 v185, v88, v88, v185
	v_fma_f32 v186, v89, v89, v186
	v_fma_f32 v187, v90, v90, v187
	v_fma_f32 v188, v91, v91, v188
	s_waitcnt vmcnt(43)
	v_lshlrev_b32_e32 v174, 16, v110
	v_and_b32_e32 v175, 0xffff0000, v110
	v_lshlrev_b32_e32 v176, 16, v111
	v_and_b32_e32 v177, 0xffff0000, v111
	v_mul_f32_e32 v174, v183, v174
	v_mul_f32_e32 v175, v183, v175
	v_mul_f32_e32 v176, v183, v176
	v_mul_f32_e32 v177, v183, v177
	v_fma_f32 v92, v28, v174, v92
	v_fma_f32 v93, v29, v175, v93
	v_fma_f32 v94, v30, v176, v94
	v_fma_f32 v95, v31, v177, v95
	global_store_dwordx4 v166, v[92:95], s[36:37] offset:3072 nt
	v_fma_f32 v185, v92, v92, v185
	v_fma_f32 v186, v93, v93, v186
	v_fma_f32 v187, v94, v94, v187
	v_fma_f32 v188, v95, v95, v188
	v_add_f32_e32 v185, v185, v186
	v_add_f32_e32 v187, v187, v188
	v_add_f32_e32 v185, v185, v187
	s_nop 1
	v_add_f32_dpp v185, v185, v185 quad_perm:[1,0,3,2] row_mask:0xf bank_mask:0xf
	s_nop 1
	v_add_f32_dpp v185, v185, v185 quad_perm:[2,3,0,1] row_mask:0xf bank_mask:0xf
	s_nop 1
	v_add_f32_dpp v185, v185, v185 row_half_mirror row_mask:0xf bank_mask:0xf
	s_nop 1
	v_add_f32_dpp v185, v185, v185 row_mirror row_mask:0xf bank_mask:0xf
	s_nop 1
	v_readlane_b32 s24, v185, 0
	v_readlane_b32 s25, v185, 16
	v_readlane_b32 s26, v185, 32
	v_readlane_b32 s27, v185, 48
	v_mov_b32_e32 v184, s24
	v_add_f32_e32 v184, s25, v184
	v_add_f32_e32 v184, s26, v184
	v_add_f32_e32 v184, s27, v184
	v_fmamk_f32 v184, v184, 0x3a000000, v182
	v_rsq_f32_e32 v184, v184
	s_nop 0
	v_mul_f32_e32 v174, v184, v64
	v_mul_f32_e32 v175, v184, v65
	v_mul_f32_e32 v176, v184, v66
	v_mul_f32_e32 v177, v184, v67
	v_mul_f32_e32 v174, v174, v32
	v_mul_f32_e32 v175, v175, v33
	v_mul_f32_e32 v176, v176, v34
	v_mul_f32_e32 v177, v177, v35
	v_cvt_pk_bf16_f32 v96, v174, v175
	v_cvt_pk_bf16_f32 v97, v176, v177
	global_store_dwordx2 v181, v[96:97], s[38:39] offset:0
	v_mul_f32_e32 v174, v184, v68
	v_mul_f32_e32 v175, v184, v69
	v_mul_f32_e32 v176, v184, v70
	v_mul_f32_e32 v177, v184, v71
	v_mul_f32_e32 v174, v174, v36
	v_mul_f32_e32 v175, v175, v37
	v_mul_f32_e32 v176, v176, v38
	v_mul_f32_e32 v177, v177, v39
	v_cvt_pk_bf16_f32 v98, v174, v175
	v_cvt_pk_bf16_f32 v99, v176, v177
	global_store_dwordx2 v181, v[98:99], s[38:39] offset:512
	v_mul_f32_e32 v174, v184, v72
	v_mul_f32_e32 v175, v184, v73
	v_mul_f32_e32 v176, v184, v74
	v_mul_f32_e32 v177, v184, v75
	v_mul_f32_e32 v174, v174, v40
	v_mul_f32_e32 v175, v175, v41
	v_mul_f32_e32 v176, v176, v42
	v_mul_f32_e32 v177, v177, v43
	v_cvt_pk_bf16_f32 v100, v174, v175
	v_cvt_pk_bf16_f32 v101, v176, v177
	global_store_dwordx2 v181, v[100:101], s[38:39] offset:1024
	v_mul_f32_e32 v174, v184, v76
	v_mul_f32_e32 v175, v184, v77
	v_mul_f32_e32 v176, v184, v78
	v_mul_f32_e32 v177, v184, v79
	v_mul_f32_e32 v174, v174, v44
	v_mul_f32_e32 v175, v175, v45
	v_mul_f32_e32 v176, v176, v46
	v_mul_f32_e32 v177, v177, v47
	v_cvt_pk_bf16_f32 v102, v174, v175
	v_cvt_pk_bf16_f32 v103, v176, v177
	global_store_dwordx2 v181, v[102:103], s[38:39] offset:1536
	v_mul_f32_e32 v174, v184, v80
	v_mul_f32_e32 v175, v184, v81
	v_mul_f32_e32 v176, v184, v82
	v_mul_f32_e32 v177, v184, v83
	v_mul_f32_e32 v174, v174, v48
	v_mul_f32_e32 v175, v175, v49
	v_mul_f32_e32 v176, v176, v50
	v_mul_f32_e32 v177, v177, v51
	v_cvt_pk_bf16_f32 v104, v174, v175
	v_cvt_pk_bf16_f32 v105, v176, v177
	global_store_dwordx2 v181, v[104:105], s[38:39] offset:2048
	v_mul_f32_e32 v174, v184, v84
	v_mul_f32_e32 v175, v184, v85
	v_mul_f32_e32 v176, v184, v86
	v_mul_f32_e32 v177, v184, v87
	v_mul_f32_e32 v174, v174, v52
	v_mul_f32_e32 v175, v175, v53
	v_mul_f32_e32 v176, v176, v54
	v_mul_f32_e32 v177, v177, v55
	v_cvt_pk_bf16_f32 v106, v174, v175
	v_cvt_pk_bf16_f32 v107, v176, v177
	global_store_dwordx2 v181, v[106:107], s[38:39] offset:2560
	v_mul_f32_e32 v174, v184, v88
	v_mul_f32_e32 v175, v184, v89
	v_mul_f32_e32 v176, v184, v90
	v_mul_f32_e32 v177, v184, v91
	v_mul_f32_e32 v174, v174, v56
	v_mul_f32_e32 v175, v175, v57
	v_mul_f32_e32 v176, v176, v58
	v_mul_f32_e32 v177, v177, v59
	v_cvt_pk_bf16_f32 v108, v174, v175
	v_cvt_pk_bf16_f32 v109, v176, v177
	global_store_dwordx2 v181, v[108:109], s[38:39] offset:3072
	v_mul_f32_e32 v174, v184, v92
	v_mul_f32_e32 v175, v184, v93
	v_mul_f32_e32 v176, v184, v94
	v_mul_f32_e32 v177, v184, v95
	v_mul_f32_e32 v174, v174, v60
	v_mul_f32_e32 v175, v175, v61
	v_mul_f32_e32 v176, v176, v62
	v_mul_f32_e32 v177, v177, v63
	v_cvt_pk_bf16_f32 v110, v174, v175
	v_cvt_pk_bf16_f32 v111, v176, v177
	global_store_dwordx2 v181, v[110:111], s[38:39] offset:3584
	s_waitcnt vmcnt(51)
	v_cvt_pk_bf16_f32 v114, v114, v115
	v_cvt_pk_bf16_f32 v115, v116, v117
	global_store_dwordx2 v181, v[114:115], s[40:41]
	s_add_i32 s30, s30, s82
	s_cmpk_gt_i32 s30, 0x7fff
	s_cbranch_scc1 .Lp5b_done
	s_branch .Lp5b_loop
; __device__ __forceinline__ unsigned xb_ld(unsigned* p)              { return __hip_atomic_load(p, __ATOMIC_RELAXED, __HIP_MEMORY_SCOPE_AGENT); }
; __device__ __forceinline__ void xcd_barrier_complete(unsigned* bar, unsigned x, unsigned& nloc, unsigned& nx) {
;     const unsigned G = gridDim.x * gridDim.y * gridDim.z;
;     unsigned sum, cnt, mine, sp = 0u;
;     for (;;) {
;         sum = 0u; cnt = 0u; mine = 0u;
; #pragma unroll
;         for (unsigned j = 0; j < 16; ++j) { const unsigned c = xb_ld(&bar[XB_XCNT(j)]); sum += c; cnt += (c > 0u) ? 1u : 0u; mine = (j == x) ? c : mine; }
; __device__ __forceinline__ void xcd_barrier(const XcdBarrier& b) {
;     asm volatile("s_waitcnt vmcnt(0)" ::: "memory");
;     __syncthreads();
;     if (threadIdx.x == 0) {
;         unsigned* bar = b.bar;
;         __builtin_amdgcn_s_waitcnt(0);
;         unsigned nloc = b.st[0], nx = b.st[1];
;         if (nloc == 0u) { xcd_barrier_complete(bar, b.x, nloc, nx); b.st[0] = nloc; b.st[1] = nx; }
.Lp5b_done:
.LBB0_1229:
	s_waitcnt vmcnt(0)
	s_barrier
	s_mov_b64 s[8:9], exec
	v_readlane_b32 s10, v246, 0
	v_readlane_b32 s11, v246, 1
	s_and_b64 s[10:11], s[8:9], s[10:11]
	s_mov_b64 exec, s[10:11]
	s_cbranch_execz .LBB0_1281
	s_add_i32 s2, 0, 0x20040
	v_mov_b32_e32 v0, s2
	s_waitcnt vmcnt(0) expcnt(0) lgkmcnt(0)
	ds_read_b32 v2, v0
	s_add_i32 s2, 0, 0x20044
	v_mov_b32_e32 v0, s2
	ds_read_b32 v0, v0
	s_waitcnt lgkmcnt(1)
	v_cmp_ne_u32_e32 vcc, 0, v2
	s_cbranch_vccnz .LBB0_1245
	v_readlane_b32 s10, v246, 2
	v_readlane_b32 s11, v246, 3
	s_mul_i32 s2, s11, s3
	s_mul_i32 s2, s2, s10
	s_add_u32 s10, s74, 0xc0200
	s_addc_u32 s11, s75, 0
	s_add_u32 s12, s74, 0xc0400
	s_addc_u32 s13, s75, 0
	s_add_u32 s14, s74, 0xc0500
	s_addc_u32 s15, s75, 0
	s_add_u32 s16, s74, 0xc0600
	s_addc_u32 s17, s75, 0
	s_add_u32 s18, s74, 0xc0700
	s_addc_u32 s19, s75, 0
	s_add_u32 s20, s74, 0xc0800
	s_addc_u32 s21, s75, 0
	s_add_u32 s22, s74, 0xc0900
	s_addc_u32 s23, s75, 0
	s_add_u32 s24, s74, 0xc0a00
	s_addc_u32 s25, s75, 0
	s_add_u32 s26, s74, 0xc0b00
	s_addc_u32 s27, s75, 0
	s_add_u32 s28, s74, 0xc0c00
	s_addc_u32 s29, s75, 0
	s_add_u32 s30, s74, 0xc0d00
	s_addc_u32 s31, s75, 0
	s_add_u32 s34, s74, 0xc0e00
	s_addc_u32 s35, s75, 0
	s_add_u32 s36, s74, 0xc0f00
	s_addc_u32 s37, s75, 0
	s_add_u32 s38, s74, 0xc1000
	s_addc_u32 s39, s75, 0
	s_add_u32 s40, s74, 0xc1100
	s_addc_u32 s41, s75, 0
	s_add_u32 s42, s74, 0xc1200
	s_addc_u32 s43, s75, 0
	s_add_u32 s44, s74, 0xc1300
	s_addc_u32 s45, s75, 0
	s_mov_b32 s33, 1
	v_mov_b32_e32 v16, 0
	s_branch .LBB0_1233

; __device__ __forceinline__ unsigned pk2(float lo, float hi) { return pg8::cvt_pk_bf16(lo, hi); }
; __device__ __forceinline__ float bf_lo(unsigned w) { return __uint_as_float(w << 16); }
; __device__ __forceinline__ float bf_hi(unsigned w) { return __uint_as_float(w & 0xffff0000u); }
; #define INP(i) ((const float*)(const GAS float*)KARG(8 * (i)))
; __global__ void __launch_bounds__(512, 2) fwd(Params P) {
;     ...
;     if (PHASE_MASK & (1 << 9)) {
;         const f32x4* g1 = (const f32x4*)INP(16) + lane;
;         for (int m = gw; m < T_TOK; m += NGW) {
;             const float rsd = __builtin_amdgcn_rsqf(ssq_d[m] * (1.f / DM) + EPS);
;             const u32x2* dr = (const u32x2*)(DN + (size_t)m * DM) + lane;
;             f32x4* orow = (f32x4*)(OUT_P + (size_t)m * DM) + lane; u32x2* o = (u32x2*)(XN + (size_t)m * DM) + lane;
; #pragma unroll
;             for (int j = 0; j < 8; ++j) { const f32x4 xv = __builtin_nontemporal_load(&orow[64 * j]); const u32x2 dw = __builtin_nontemporal_load(&dr[64 * j]); const f32x4 g = g1[64 * j];
;                 f32x4 t; t.x = xv.x + bf_lo(dw.x) * rsd * g.x; t.y = xv.y + bf_hi(dw.x) * rsd * g.y; t.z = xv.z + bf_lo(dw.y) * rsd * g.z; t.w = xv.w + bf_hi(dw.y) * rsd * g.w;
;                 orow[64 * j] = t; u32x2 w; w.x = pk2(t.x, t.y); w.y = pk2(t.z, t.w); o[64 * j] = w; }
.LBB0_1489:
	s_or_b64 exec, exec, s[8:9]
	s_mov_b64 s[8:9], s[0:1]
	s_and_b64 vcc, exec, s[6:7]
	s_waitcnt lgkmcnt(0)
	s_barrier
	s_cbranch_vccnz .LBB0_1492
	s_load_dwordx2 s[6:7], s[0:1], 0x80
	s_load_dwordx2 s[8:9], s[0:1], 0xa0
	s_load_dwordx2 s[10:11], s[0:1], 0xa8
	v_mov_b32_e32 v167, 0
	v_lshlrev_b32_e32 v32, 3, v179
	v_mov_b32_e32 v33, 0x358637bd
	s_waitcnt lgkmcnt(0)
	s_add_u32 s8, s8, 0x1000
	s_addc_u32 s9, s9, 0
	s_add_u32 s12, s10, 0x60000
	s_addc_u32 s13, s11, 0
	s_add_u32 s14, s10, 0x30000000
	s_addc_u32 s15, s11, 0
	s_add_u32 s16, s10, 0x8000000
	s_addc_u32 s17, s11, 0
	s_add_u32 s28, s6, 0x1000
	s_addc_u32 s29, s7, 0
	global_load_dwordx4 v[0:3], v166, s[6:7] offset:0
	global_load_dwordx4 v[4:7], v166, s[6:7] offset:1024
	global_load_dwordx4 v[8:11], v166, s[6:7] offset:2048
	global_load_dwordx4 v[12:15], v166, s[6:7] offset:3072
	global_load_dwordx4 v[16:19], v166, s[28:29] offset:0
	global_load_dwordx4 v[20:23], v166, s[28:29] offset:1024
	global_load_dwordx4 v[24:27], v166, s[28:29] offset:2048
	global_load_dwordx4 v[28:31], v166, s[28:29] offset:3072
	s_lshl_b32 s30, s80, 13
	s_add_u32 s18, s8, s30
	s_addc_u32 s19, s9, 0
	s_lshl_b32 s30, s80, 12
	s_add_u32 s20, s14, s30
	s_addc_u32 s21, s15, 0
	s_lshl_b32 s30, s80, 2
	s_add_u32 s22, s12, s30
	s_addc_u32 s23, s13, 0
	global_load_dword v88, v167, s[22:23]
	global_load_dwordx4 v[40:43], v166, s[18:19] offset:-4096 nt
	global_load_dwordx2 v[72:73], v32, s[20:21] offset:0 nt
	global_load_dwordx4 v[44:47], v166, s[18:19] offset:-3072 nt
	global_load_dwordx2 v[74:75], v32, s[20:21] offset:512 nt
	global_load_dwordx4 v[48:51], v166, s[18:19] offset:-2048 nt
	global_load_dwordx2 v[76:77], v32, s[20:21] offset:1024 nt
	global_load_dwordx4 v[52:55], v166, s[18:19] offset:-1024 nt
	global_load_dwordx2 v[78:79], v32, s[20:21] offset:1536 nt
	global_load_dwordx4 v[56:59], v166, s[18:19] offset:0 nt
	global_load_dwordx2 v[80:81], v32, s[20:21] offset:2048 nt
	global_load_dwordx4 v[60:63], v166, s[18:19] offset:1024 nt
	global_load_dwordx2 v[82:83], v32, s[20:21] offset:2560 nt
	global_load_dwordx4 v[64:67], v166, s[18:19] offset:2048 nt
	global_load_dwordx2 v[84:85], v32, s[20:21] offset:3072 nt
	global_load_dwordx4 v[68:71], v166, s[18:19] offset:3072 nt
	global_load_dwordx2 v[86:87], v32, s[20:21] offset:3584 nt
	s_mov_b64 s[24:25], s[18:19]
	s_lshl_b32 s30, s80, 12
	s_add_u32 s26, s16, s30
	s_addc_u32 s27, s17, 0
	s_add_i32 s31, s80, s82
	s_cmpk_gt_i32 s31, 0x7fff
	s_cselect_b32 s31, s80, s31
	s_lshl_b32 s30, s31, 13
	s_add_u32 s18, s8, s30
	s_addc_u32 s19, s9, 0
	s_lshl_b32 s30, s31, 12
	s_add_u32 s20, s14, s30
	s_addc_u32 s21, s15, 0
	s_lshl_b32 s30, s31, 2
	s_add_u32 s22, s12, s30
	s_addc_u32 s23, s13, 0
	global_load_dword v144, v167, s[22:23]
	global_load_dwordx4 v[96:99], v166, s[18:19] offset:-4096 nt
	global_load_dwordx2 v[128:129], v32, s[20:21] offset:0 nt
	global_load_dwordx4 v[100:103], v166, s[18:19] offset:-3072 nt
	global_load_dwordx2 v[130:131], v32, s[20:21] offset:512 nt
	global_load_dwordx4 v[104:107], v166, s[18:19] offset:-2048 nt
	global_load_dwordx2 v[132:133], v32, s[20:21] offset:1024 nt
	global_load_dwordx4 v[108:111], v166, s[18:19] offset:-1024 nt
	global_load_dwordx2 v[134:135], v32, s[20:21] offset:1536 nt
	global_load_dwordx4 v[112:115], v166, s[18:19] offset:0 nt
	global_load_dwordx2 v[136:137], v32, s[20:21] offset:2048 nt
	global_load_dwordx4 v[116:119], v166, s[18:19] offset:1024 nt
	global_load_dwordx2 v[138:139], v32, s[20:21] offset:2560 nt
	global_load_dwordx4 v[120:123], v166, s[18:19] offset:2048 nt
	global_load_dwordx2 v[140:141], v32, s[20:21] offset:3072 nt
	global_load_dwordx4 v[124:127], v166, s[18:19] offset:3072 nt
	global_load_dwordx2 v[142:143], v32, s[20:21] offset:3584 nt
	s_waitcnt vmcnt(31)
	v_fmamk_f32 v34, v88, 0x3a000000, v33
	v_rsq_f32_e32 v34, v34
	v_lshlrev_b32_e32 v35, 16, v72
	v_and_b32_e32 v36, 0xffff0000, v72
	v_lshlrev_b32_e32 v37, 16, v73
	v_and_b32_e32 v38, 0xffff0000, v73
	v_mul_f32_e32 v35, v34, v35
	v_mul_f32_e32 v36, v34, v36
	v_mul_f32_e32 v37, v34, v37
	v_mul_f32_e32 v38, v34, v38
	v_fma_f32 v40, v0, v35, v40
	v_fma_f32 v41, v1, v36, v41
	v_fma_f32 v42, v2, v37, v42
	v_fma_f32 v43, v3, v38, v43
	global_store_dwordx4 v166, v[40:43], s[24:25] offset:-4096
	v_cvt_pk_bf16_f32 v72, v40, v41
	v_cvt_pk_bf16_f32 v73, v42, v43
	global_store_dwordx2 v32, v[72:73], s[26:27] offset:0
	s_waitcnt vmcnt(31)
	v_lshlrev_b32_e32 v35, 16, v74
	v_and_b32_e32 v36, 0xffff0000, v74
	v_lshlrev_b32_e32 v37, 16, v75
	v_and_b32_e32 v38, 0xffff0000, v75
	v_mul_f32_e32 v35, v34, v35
	v_mul_f32_e32 v36, v34, v36
	v_mul_f32_e32 v37, v34, v37
	v_mul_f32_e32 v38, v34, v38
	v_fma_f32 v44, v4, v35, v44
	v_fma_f32 v45, v5, v36, v45
	v_fma_f32 v46, v6, v37, v46
	v_fma_f32 v47, v7, v38, v47
	global_store_dwordx4 v166, v[44:47], s[24:25] offset:-3072
	v_cvt_pk_bf16_f32 v74, v44, v45
	v_cvt_pk_bf16_f32 v75, v46, v47
	global_store_dwordx2 v32, v[74:75], s[26:27] offset:512
	s_waitcnt vmcnt(31)
	v_lshlrev_b32_e32 v35, 16, v76
	v_and_b32_e32 v36, 0xffff0000, v76
	v_lshlrev_b32_e32 v37, 16, v77
	v_and_b32_e32 v38, 0xffff0000, v77
	v_mul_f32_e32 v35, v34, v35
	v_mul_f32_e32 v36, v34, v36
	v_mul_f32_e32 v37, v34, v37
	v_mul_f32_e32 v38, v34, v38
	v_fma_f32 v48, v8, v35, v48
	v_fma_f32 v49, v9, v36, v49
	v_fma_f32 v50, v10, v37, v50
	v_fma_f32 v51, v11, v38, v51
	global_store_dwordx4 v166, v[48:51], s[24:25] offset:-2048
	v_cvt_pk_bf16_f32 v76, v48, v49
	v_cvt_pk_bf16_f32 v77, v50, v51
	global_store_dwordx2 v32, v[76:77], s[26:27] offset:1024
	s_waitcnt vmcnt(31)
; __device__ __forceinline__ unsigned pk2(float lo, float hi) { return pg8::cvt_pk_bf16(lo, hi); }
; __device__ __forceinline__ float bf_lo(unsigned w) { return __uint_as_float(w << 16); }
; __device__ __forceinline__ float bf_hi(unsigned w) { return __uint_as_float(w & 0xffff0000u); }
; __global__ void __launch_bounds__(512, 2) fwd(Params P) {
;     ...
;         for (int m = gw; m < T_TOK; m += NGW) {
;             const float rsd = __builtin_amdgcn_rsqf(ssq_d[m] * (1.f / DM) + EPS);
;             const u32x2* dr = (const u32x2*)(DN + (size_t)m * DM) + lane;
;             f32x4* orow = (f32x4*)(OUT_P + (size_t)m * DM) + lane; u32x2* o = (u32x2*)(XN + (size_t)m * DM) + lane;
; #pragma unroll
;             for (int j = 0; j < 8; ++j) { const f32x4 xv = __builtin_nontemporal_load(&orow[64 * j]); const u32x2 dw = __builtin_nontemporal_load(&dr[64 * j]); const f32x4 g = g1[64 * j];
;                 f32x4 t; t.x = xv.x + bf_lo(dw.x) * rsd * g.x; t.y = xv.y + bf_hi(dw.x) * rsd * g.y; t.z = xv.z + bf_lo(dw.y) * rsd * g.z; t.w = xv.w + bf_hi(dw.y) * rsd * g.w;
;                 orow[64 * j] = t; u32x2 w; w.x = pk2(t.x, t.y); w.y = pk2(t.z, t.w); o[64 * j] = w; }
	v_lshlrev_b32_e32 v35, 16, v78
	v_and_b32_e32 v36, 0xffff0000, v78
	v_lshlrev_b32_e32 v37, 16, v79
	v_and_b32_e32 v38, 0xffff0000, v79
	v_mul_f32_e32 v35, v34, v35
	v_mul_f32_e32 v36, v34, v36
	v_mul_f32_e32 v37, v34, v37
	v_mul_f32_e32 v38, v34, v38
	v_fma_f32 v52, v12, v35, v52
	v_fma_f32 v53, v13, v36, v53
	v_fma_f32 v54, v14, v37, v54
	v_fma_f32 v55, v15, v38, v55
	global_store_dwordx4 v166, v[52:55], s[24:25] offset:-1024
	v_cvt_pk_bf16_f32 v78, v52, v53
	v_cvt_pk_bf16_f32 v79, v54, v55
	global_store_dwordx2 v32, v[78:79], s[26:27] offset:1536
	s_waitcnt vmcnt(31)
	v_lshlrev_b32_e32 v35, 16, v80
	v_and_b32_e32 v36, 0xffff0000, v80
	v_lshlrev_b32_e32 v37, 16, v81
	v_and_b32_e32 v38, 0xffff0000, v81
	v_mul_f32_e32 v35, v34, v35
	v_mul_f32_e32 v36, v34, v36
	v_mul_f32_e32 v37, v34, v37
	v_mul_f32_e32 v38, v34, v38
	v_fma_f32 v56, v16, v35, v56
	v_fma_f32 v57, v17, v36, v57
	v_fma_f32 v58, v18, v37, v58
	v_fma_f32 v59, v19, v38, v59
	global_store_dwordx4 v166, v[56:59], s[24:25] offset:0
	v_cvt_pk_bf16_f32 v80, v56, v57
	v_cvt_pk_bf16_f32 v81, v58, v59
	global_store_dwordx2 v32, v[80:81], s[26:27] offset:2048
	s_waitcnt vmcnt(31)
	v_lshlrev_b32_e32 v35, 16, v82
	v_and_b32_e32 v36, 0xffff0000, v82
	v_lshlrev_b32_e32 v37, 16, v83
	v_and_b32_e32 v38, 0xffff0000, v83
	v_mul_f32_e32 v35, v34, v35
	v_mul_f32_e32 v36, v34, v36
	v_mul_f32_e32 v37, v34, v37
	v_mul_f32_e32 v38, v34, v38
	v_fma_f32 v60, v20, v35, v60
	v_fma_f32 v61, v21, v36, v61
	v_fma_f32 v62, v22, v37, v62
	v_fma_f32 v63, v23, v38, v63
	global_store_dwordx4 v166, v[60:63], s[24:25] offset:1024
	v_cvt_pk_bf16_f32 v82, v60, v61
	v_cvt_pk_bf16_f32 v83, v62, v63
	global_store_dwordx2 v32, v[82:83], s[26:27] offset:2560
	s_waitcnt vmcnt(31)
	v_lshlrev_b32_e32 v35, 16, v84
	v_and_b32_e32 v36, 0xffff0000, v84
	v_lshlrev_b32_e32 v37, 16, v85
	v_and_b32_e32 v38, 0xffff0000, v85
	v_mul_f32_e32 v35, v34, v35
	v_mul_f32_e32 v36, v34, v36
	v_mul_f32_e32 v37, v34, v37
	v_mul_f32_e32 v38, v34, v38
	v_fma_f32 v64, v24, v35, v64
	v_fma_f32 v65, v25, v36, v65
	v_fma_f32 v66, v26, v37, v66
	v_fma_f32 v67, v27, v38, v67
	global_store_dwordx4 v166, v[64:67], s[24:25] offset:2048
	v_cvt_pk_bf16_f32 v84, v64, v65
	v_cvt_pk_bf16_f32 v85, v66, v67
	global_store_dwordx2 v32, v[84:85], s[26:27] offset:3072
	s_waitcnt vmcnt(31)
	v_lshlrev_b32_e32 v35, 16, v86
	v_and_b32_e32 v36, 0xffff0000, v86
	v_lshlrev_b32_e32 v37, 16, v87
	v_and_b32_e32 v38, 0xffff0000, v87
	v_mul_f32_e32 v35, v34, v35
	v_mul_f32_e32 v36, v34, v36
	v_mul_f32_e32 v37, v34, v37
	v_mul_f32_e32 v38, v34, v38
	v_fma_f32 v68, v28, v35, v68
	v_fma_f32 v69, v29, v36, v69
	v_fma_f32 v70, v30, v37, v70
	v_fma_f32 v71, v31, v38, v71
	global_store_dwordx4 v166, v[68:71], s[24:25] offset:3072
	v_cvt_pk_bf16_f32 v86, v68, v69
	v_cvt_pk_bf16_f32 v87, v70, v71
	global_store_dwordx2 v32, v[86:87], s[26:27] offset:3584
	s_add_i32 s80, s80, s82
	s_cmpk_gt_i32 s80, 0x7fff
	s_cbranch_scc1 .Lp7b_done
.Lp7b_loop:
	s_mov_b64 s[24:25], s[18:19]
	s_lshl_b32 s30, s80, 12
	s_add_u32 s26, s16, s30
	s_addc_u32 s27, s17, 0
	s_add_i32 s31, s80, s82
	s_cmpk_gt_i32 s31, 0x7fff
	s_cselect_b32 s31, s80, s31
	s_lshl_b32 s30, s31, 13
	s_add_u32 s18, s8, s30
	s_addc_u32 s19, s9, 0
	s_lshl_b32 s30, s31, 12
	s_add_u32 s20, s14, s30
	s_addc_u32 s21, s15, 0
	s_lshl_b32 s30, s31, 2
	s_add_u32 s22, s12, s30
	s_addc_u32 s23, s13, 0
	global_load_dword v88, v167, s[22:23]
	global_load_dwordx4 v[40:43], v166, s[18:19] offset:-4096 nt
	global_load_dwordx2 v[72:73], v32, s[20:21] offset:0 nt
	global_load_dwordx4 v[44:47], v166, s[18:19] offset:-3072 nt
	global_load_dwordx2 v[74:75], v32, s[20:21] offset:512 nt
	global_load_dwordx4 v[48:51], v166, s[18:19] offset:-2048 nt
	global_load_dwordx2 v[76:77], v32, s[20:21] offset:1024 nt
	global_load_dwordx4 v[52:55], v166, s[18:19] offset:-1024 nt
	global_load_dwordx2 v[78:79], v32, s[20:21] offset:1536 nt
	global_load_dwordx4 v[56:59], v166, s[18:19] offset:0 nt
	global_load_dwordx2 v[80:81], v32, s[20:21] offset:2048 nt
	global_load_dwordx4 v[60:63], v166, s[18:19] offset:1024 nt
	global_load_dwordx2 v[82:83], v32, s[20:21] offset:2560 nt
	global_load_dwordx4 v[64:67], v166, s[18:19] offset:2048 nt
	global_load_dwordx2 v[84:85], v32, s[20:21] offset:3072 nt
	global_load_dwordx4 v[68:71], v166, s[18:19] offset:3072 nt
	global_load_dwordx2 v[86:87], v32, s[20:21] offset:3584 nt
	s_waitcnt vmcnt(47)
	v_fmamk_f32 v34, v144, 0x3a000000, v33
	v_rsq_f32_e32 v34, v34
	v_lshlrev_b32_e32 v35, 16, v128
	v_and_b32_e32 v36, 0xffff0000, v128
	v_lshlrev_b32_e32 v37, 16, v129
	v_and_b32_e32 v38, 0xffff0000, v129
	v_mul_f32_e32 v35, v34, v35
	v_mul_f32_e32 v36, v34, v36
	v_mul_f32_e32 v37, v34, v37
	v_mul_f32_e32 v38, v34, v38
	v_fma_f32 v96, v0, v35, v96
	v_fma_f32 v97, v1, v36, v97
	v_fma_f32 v98, v2, v37, v98
	v_fma_f32 v99, v3, v38, v99
	global_store_dwordx4 v166, v[96:99], s[24:25] offset:-4096
	v_cvt_pk_bf16_f32 v128, v96, v97
	v_cvt_pk_bf16_f32 v129, v98, v99
	global_store_dwordx2 v32, v[128:129], s[26:27] offset:0
	s_waitcnt vmcnt(47)
	v_lshlrev_b32_e32 v35, 16, v130
	v_and_b32_e32 v36, 0xffff0000, v130
	v_lshlrev_b32_e32 v37, 16, v131
	v_and_b32_e32 v38, 0xffff0000, v131
	v_mul_f32_e32 v35, v34, v35
	v_mul_f32_e32 v36, v34, v36
	v_mul_f32_e32 v37, v34, v37
	v_mul_f32_e32 v38, v34, v38
	v_fma_f32 v100, v4, v35, v100
	v_fma_f32 v101, v5, v36, v101
	v_fma_f32 v102, v6, v37, v102
	v_fma_f32 v103, v7, v38, v103
	global_store_dwordx4 v166, v[100:103], s[24:25] offset:-3072
	v_cvt_pk_bf16_f32 v130, v100, v101
	v_cvt_pk_bf16_f32 v131, v102, v103
	global_store_dwordx2 v32, v[130:131], s[26:27] offset:512
	s_waitcnt vmcnt(47)
; __device__ __forceinline__ unsigned pk2(float lo, float hi) { return pg8::cvt_pk_bf16(lo, hi); }
; __device__ __forceinline__ float bf_lo(unsigned w) { return __uint_as_float(w << 16); }
; __device__ __forceinline__ float bf_hi(unsigned w) { return __uint_as_float(w & 0xffff0000u); }
; __global__ void __launch_bounds__(512, 2) fwd(Params P) {
;     ...
;         for (int m = gw; m < T_TOK; m += NGW) {
;             const float rsd = __builtin_amdgcn_rsqf(ssq_d[m] * (1.f / DM) + EPS);
;             const u32x2* dr = (const u32x2*)(DN + (size_t)m * DM) + lane;
;             f32x4* orow = (f32x4*)(OUT_P + (size_t)m * DM) + lane; u32x2* o = (u32x2*)(XN + (size_t)m * DM) + lane;
; #pragma unroll
;             for (int j = 0; j < 8; ++j) { const f32x4 xv = __builtin_nontemporal_load(&orow[64 * j]); const u32x2 dw = __builtin_nontemporal_load(&dr[64 * j]); const f32x4 g = g1[64 * j];
;                 f32x4 t; t.x = xv.x + bf_lo(dw.x) * rsd * g.x; t.y = xv.y + bf_hi(dw.x) * rsd * g.y; t.z = xv.z + bf_lo(dw.y) * rsd * g.z; t.w = xv.w + bf_hi(dw.y) * rsd * g.w;
;                 orow[64 * j] = t; u32x2 w; w.x = pk2(t.x, t.y); w.y = pk2(t.z, t.w); o[64 * j] = w; }
	v_lshlrev_b32_e32 v35, 16, v132
	v_and_b32_e32 v36, 0xffff0000, v132
	v_lshlrev_b32_e32 v37, 16, v133
	v_and_b32_e32 v38, 0xffff0000, v133
	v_mul_f32_e32 v35, v34, v35
	v_mul_f32_e32 v36, v34, v36
	v_mul_f32_e32 v37, v34, v37
	v_mul_f32_e32 v38, v34, v38
	v_fma_f32 v104, v8, v35, v104
	v_fma_f32 v105, v9, v36, v105
	v_fma_f32 v106, v10, v37, v106
	v_fma_f32 v107, v11, v38, v107
	global_store_dwordx4 v166, v[104:107], s[24:25] offset:-2048
	v_cvt_pk_bf16_f32 v132, v104, v105
	v_cvt_pk_bf16_f32 v133, v106, v107
	global_store_dwordx2 v32, v[132:133], s[26:27] offset:1024
	s_waitcnt vmcnt(47)
	v_lshlrev_b32_e32 v35, 16, v134
	v_and_b32_e32 v36, 0xffff0000, v134
	v_lshlrev_b32_e32 v37, 16, v135
	v_and_b32_e32 v38, 0xffff0000, v135
	v_mul_f32_e32 v35, v34, v35
	v_mul_f32_e32 v36, v34, v36
	v_mul_f32_e32 v37, v34, v37
	v_mul_f32_e32 v38, v34, v38
	v_fma_f32 v108, v12, v35, v108
	v_fma_f32 v109, v13, v36, v109
	v_fma_f32 v110, v14, v37, v110
	v_fma_f32 v111, v15, v38, v111
	global_store_dwordx4 v166, v[108:111], s[24:25] offset:-1024
	v_cvt_pk_bf16_f32 v134, v108, v109
	v_cvt_pk_bf16_f32 v135, v110, v111
	global_store_dwordx2 v32, v[134:135], s[26:27] offset:1536
	s_waitcnt vmcnt(47)
	v_lshlrev_b32_e32 v35, 16, v136
	v_and_b32_e32 v36, 0xffff0000, v136
	v_lshlrev_b32_e32 v37, 16, v137
	v_and_b32_e32 v38, 0xffff0000, v137
	v_mul_f32_e32 v35, v34, v35
	v_mul_f32_e32 v36, v34, v36
	v_mul_f32_e32 v37, v34, v37
	v_mul_f32_e32 v38, v34, v38
	v_fma_f32 v112, v16, v35, v112
	v_fma_f32 v113, v17, v36, v113
	v_fma_f32 v114, v18, v37, v114
	v_fma_f32 v115, v19, v38, v115
	global_store_dwordx4 v166, v[112:115], s[24:25] offset:0
	v_cvt_pk_bf16_f32 v136, v112, v113
	v_cvt_pk_bf16_f32 v137, v114, v115
	global_store_dwordx2 v32, v[136:137], s[26:27] offset:2048
	s_waitcnt vmcnt(47)
	v_lshlrev_b32_e32 v35, 16, v138
	v_and_b32_e32 v36, 0xffff0000, v138
	v_lshlrev_b32_e32 v37, 16, v139
	v_and_b32_e32 v38, 0xffff0000, v139
	v_mul_f32_e32 v35, v34, v35
	v_mul_f32_e32 v36, v34, v36
	v_mul_f32_e32 v37, v34, v37
	v_mul_f32_e32 v38, v34, v38
	v_fma_f32 v116, v20, v35, v116
	v_fma_f32 v117, v21, v36, v117
	v_fma_f32 v118, v22, v37, v118
	v_fma_f32 v119, v23, v38, v119
	global_store_dwordx4 v166, v[116:119], s[24:25] offset:1024
	v_cvt_pk_bf16_f32 v138, v116, v117
	v_cvt_pk_bf16_f32 v139, v118, v119
	global_store_dwordx2 v32, v[138:139], s[26:27] offset:2560
	s_waitcnt vmcnt(47)
	v_lshlrev_b32_e32 v35, 16, v140
	v_and_b32_e32 v36, 0xffff0000, v140
	v_lshlrev_b32_e32 v37, 16, v141
	v_and_b32_e32 v38, 0xffff0000, v141
	v_mul_f32_e32 v35, v34, v35
	v_mul_f32_e32 v36, v34, v36
	v_mul_f32_e32 v37, v34, v37
	v_mul_f32_e32 v38, v34, v38
	v_fma_f32 v120, v24, v35, v120
	v_fma_f32 v121, v25, v36, v121
	v_fma_f32 v122, v26, v37, v122
	v_fma_f32 v123, v27, v38, v123
	global_store_dwordx4 v166, v[120:123], s[24:25] offset:2048
	v_cvt_pk_bf16_f32 v140, v120, v121
	v_cvt_pk_bf16_f32 v141, v122, v123
	global_store_dwordx2 v32, v[140:141], s[26:27] offset:3072
	s_waitcnt vmcnt(47)
	v_lshlrev_b32_e32 v35, 16, v142
	v_and_b32_e32 v36, 0xffff0000, v142
	v_lshlrev_b32_e32 v37, 16, v143
	v_and_b32_e32 v38, 0xffff0000, v143
	v_mul_f32_e32 v35, v34, v35
	v_mul_f32_e32 v36, v34, v36
	v_mul_f32_e32 v37, v34, v37
	v_mul_f32_e32 v38, v34, v38
	v_fma_f32 v124, v28, v35, v124
	v_fma_f32 v125, v29, v36, v125
	v_fma_f32 v126, v30, v37, v126
	v_fma_f32 v127, v31, v38, v127
	global_store_dwordx4 v166, v[124:127], s[24:25] offset:3072
	v_cvt_pk_bf16_f32 v142, v124, v125
	v_cvt_pk_bf16_f32 v143, v126, v127
	global_store_dwordx2 v32, v[142:143], s[26:27] offset:3584
	s_add_i32 s80, s80, s82
	s_cmpk_gt_i32 s80, 0x7fff
	s_cbranch_scc1 .Lp7b_done
	s_mov_b64 s[24:25], s[18:19]
	s_lshl_b32 s30, s80, 12
	s_add_u32 s26, s16, s30
	s_addc_u32 s27, s17, 0
	s_add_i32 s31, s80, s82
	s_cmpk_gt_i32 s31, 0x7fff
	s_cselect_b32 s31, s80, s31
	s_lshl_b32 s30, s31, 13
	s_add_u32 s18, s8, s30
	s_addc_u32 s19, s9, 0
	s_lshl_b32 s30, s31, 12
	s_add_u32 s20, s14, s30
	s_addc_u32 s21, s15, 0
	s_lshl_b32 s30, s31, 2
	s_add_u32 s22, s12, s30
	s_addc_u32 s23, s13, 0
	global_load_dword v144, v167, s[22:23]
	global_load_dwordx4 v[96:99], v166, s[18:19] offset:-4096 nt
	global_load_dwordx2 v[128:129], v32, s[20:21] offset:0 nt
	global_load_dwordx4 v[100:103], v166, s[18:19] offset:-3072 nt
	global_load_dwordx2 v[130:131], v32, s[20:21] offset:512 nt
	global_load_dwordx4 v[104:107], v166, s[18:19] offset:-2048 nt
	global_load_dwordx2 v[132:133], v32, s[20:21] offset:1024 nt
	global_load_dwordx4 v[108:111], v166, s[18:19] offset:-1024 nt
	global_load_dwordx2 v[134:135], v32, s[20:21] offset:1536 nt
	global_load_dwordx4 v[112:115], v166, s[18:19] offset:0 nt
	global_load_dwordx2 v[136:137], v32, s[20:21] offset:2048 nt
	global_load_dwordx4 v[116:119], v166, s[18:19] offset:1024 nt
	global_load_dwordx2 v[138:139], v32, s[20:21] offset:2560 nt
	global_load_dwordx4 v[120:123], v166, s[18:19] offset:2048 nt
	global_load_dwordx2 v[140:141], v32, s[20:21] offset:3072 nt
	global_load_dwordx4 v[124:127], v166, s[18:19] offset:3072 nt
	global_load_dwordx2 v[142:143], v32, s[20:21] offset:3584 nt
	s_waitcnt vmcnt(47)
	v_fmamk_f32 v34, v88, 0x3a000000, v33
	v_rsq_f32_e32 v34, v34
	v_lshlrev_b32_e32 v35, 16, v72
	v_and_b32_e32 v36, 0xffff0000, v72
	v_lshlrev_b32_e32 v37, 16, v73
	v_and_b32_e32 v38, 0xffff0000, v73
	v_mul_f32_e32 v35, v34, v35
	v_mul_f32_e32 v36, v34, v36
	v_mul_f32_e32 v37, v34, v37
	v_mul_f32_e32 v38, v34, v38
	v_fma_f32 v40, v0, v35, v40
	v_fma_f32 v41, v1, v36, v41
	v_fma_f32 v42, v2, v37, v42
	v_fma_f32 v43, v3, v38, v43
	global_store_dwordx4 v166, v[40:43], s[24:25] offset:-4096
	v_cvt_pk_bf16_f32 v72, v40, v41
	v_cvt_pk_bf16_f32 v73, v42, v43
	global_store_dwordx2 v32, v[72:73], s[26:27] offset:0
	s_waitcnt vmcnt(47)
; __device__ __forceinline__ unsigned pk2(float lo, float hi) { return pg8::cvt_pk_bf16(lo, hi); }
; __device__ __forceinline__ float bf_lo(unsigned w) { return __uint_as_float(w << 16); }
; __device__ __forceinline__ float bf_hi(unsigned w) { return __uint_as_float(w & 0xffff0000u); }
; __device__ __forceinline__ void xcd_barrier(const XcdBarrier& b) {
;     asm volatile("s_waitcnt vmcnt(0)" ::: "memory");
;     __syncthreads();
;     if (threadIdx.x == 0) {
;         unsigned* bar = b.bar;
;         __builtin_amdgcn_s_waitcnt(0);
;         unsigned nloc = b.st[0], nx = b.st[1];
;         if (nloc == 0u) { xcd_barrier_complete(bar, b.x, nloc, nx); b.st[0] = nloc; b.st[1] = nx; }
; __global__ void __launch_bounds__(512, 2) fwd(Params P) {
;     ...
;         for (int m = gw; m < T_TOK; m += NGW) {
;             const float rsd = __builtin_amdgcn_rsqf(ssq_d[m] * (1.f / DM) + EPS);
;             const u32x2* dr = (const u32x2*)(DN + (size_t)m * DM) + lane;
;             f32x4* orow = (f32x4*)(OUT_P + (size_t)m * DM) + lane; u32x2* o = (u32x2*)(XN + (size_t)m * DM) + lane;
; #pragma unroll
;             for (int j = 0; j < 8; ++j) { const f32x4 xv = __builtin_nontemporal_load(&orow[64 * j]); const u32x2 dw = __builtin_nontemporal_load(&dr[64 * j]); const f32x4 g = g1[64 * j];
;                 f32x4 t; t.x = xv.x + bf_lo(dw.x) * rsd * g.x; t.y = xv.y + bf_hi(dw.x) * rsd * g.y; t.z = xv.z + bf_lo(dw.y) * rsd * g.z; t.w = xv.w + bf_hi(dw.y) * rsd * g.w;
;                 orow[64 * j] = t; u32x2 w; w.x = pk2(t.x, t.y); w.y = pk2(t.z, t.w); o[64 * j] = w; }
;         }
;     }
	v_lshlrev_b32_e32 v35, 16, v74
	v_and_b32_e32 v36, 0xffff0000, v74
	v_lshlrev_b32_e32 v37, 16, v75
	v_and_b32_e32 v38, 0xffff0000, v75
	v_mul_f32_e32 v35, v34, v35
	v_mul_f32_e32 v36, v34, v36
	v_mul_f32_e32 v37, v34, v37
	v_mul_f32_e32 v38, v34, v38
	v_fma_f32 v44, v4, v35, v44
	v_fma_f32 v45, v5, v36, v45
	v_fma_f32 v46, v6, v37, v46
	v_fma_f32 v47, v7, v38, v47
	global_store_dwordx4 v166, v[44:47], s[24:25] offset:-3072
	v_cvt_pk_bf16_f32 v74, v44, v45
	v_cvt_pk_bf16_f32 v75, v46, v47
	global_store_dwordx2 v32, v[74:75], s[26:27] offset:512
	s_waitcnt vmcnt(47)
	v_lshlrev_b32_e32 v35, 16, v76
	v_and_b32_e32 v36, 0xffff0000, v76
	v_lshlrev_b32_e32 v37, 16, v77
	v_and_b32_e32 v38, 0xffff0000, v77
	v_mul_f32_e32 v35, v34, v35
	v_mul_f32_e32 v36, v34, v36
	v_mul_f32_e32 v37, v34, v37
	v_mul_f32_e32 v38, v34, v38
	v_fma_f32 v48, v8, v35, v48
	v_fma_f32 v49, v9, v36, v49
	v_fma_f32 v50, v10, v37, v50
	v_fma_f32 v51, v11, v38, v51
	global_store_dwordx4 v166, v[48:51], s[24:25] offset:-2048
	v_cvt_pk_bf16_f32 v76, v48, v49
	v_cvt_pk_bf16_f32 v77, v50, v51
	global_store_dwordx2 v32, v[76:77], s[26:27] offset:1024
	s_waitcnt vmcnt(47)
	v_lshlrev_b32_e32 v35, 16, v78
	v_and_b32_e32 v36, 0xffff0000, v78
	v_lshlrev_b32_e32 v37, 16, v79
	v_and_b32_e32 v38, 0xffff0000, v79
	v_mul_f32_e32 v35, v34, v35
	v_mul_f32_e32 v36, v34, v36
	v_mul_f32_e32 v37, v34, v37
	v_mul_f32_e32 v38, v34, v38
	v_fma_f32 v52, v12, v35, v52
	v_fma_f32 v53, v13, v36, v53
	v_fma_f32 v54, v14, v37, v54
	v_fma_f32 v55, v15, v38, v55
	global_store_dwordx4 v166, v[52:55], s[24:25] offset:-1024
	v_cvt_pk_bf16_f32 v78, v52, v53
	v_cvt_pk_bf16_f32 v79, v54, v55
	global_store_dwordx2 v32, v[78:79], s[26:27] offset:1536
	s_waitcnt vmcnt(47)
	v_lshlrev_b32_e32 v35, 16, v80
	v_and_b32_e32 v36, 0xffff0000, v80
	v_lshlrev_b32_e32 v37, 16, v81
	v_and_b32_e32 v38, 0xffff0000, v81
	v_mul_f32_e32 v35, v34, v35
	v_mul_f32_e32 v36, v34, v36
	v_mul_f32_e32 v37, v34, v37
	v_mul_f32_e32 v38, v34, v38
	v_fma_f32 v56, v16, v35, v56
	v_fma_f32 v57, v17, v36, v57
	v_fma_f32 v58, v18, v37, v58
	v_fma_f32 v59, v19, v38, v59
	global_store_dwordx4 v166, v[56:59], s[24:25] offset:0
	v_cvt_pk_bf16_f32 v80, v56, v57
	v_cvt_pk_bf16_f32 v81, v58, v59
	global_store_dwordx2 v32, v[80:81], s[26:27] offset:2048
	s_waitcnt vmcnt(47)
	v_lshlrev_b32_e32 v35, 16, v82
	v_and_b32_e32 v36, 0xffff0000, v82
	v_lshlrev_b32_e32 v37, 16, v83
	v_and_b32_e32 v38, 0xffff0000, v83
	v_mul_f32_e32 v35, v34, v35
	v_mul_f32_e32 v36, v34, v36
	v_mul_f32_e32 v37, v34, v37
	v_mul_f32_e32 v38, v34, v38
	v_fma_f32 v60, v20, v35, v60
	v_fma_f32 v61, v21, v36, v61
	v_fma_f32 v62, v22, v37, v62
	v_fma_f32 v63, v23, v38, v63
	global_store_dwordx4 v166, v[60:63], s[24:25] offset:1024
	v_cvt_pk_bf16_f32 v82, v60, v61
	v_cvt_pk_bf16_f32 v83, v62, v63
	global_store_dwordx2 v32, v[82:83], s[26:27] offset:2560
	s_waitcnt vmcnt(47)
	v_lshlrev_b32_e32 v35, 16, v84
	v_and_b32_e32 v36, 0xffff0000, v84
	v_lshlrev_b32_e32 v37, 16, v85
	v_and_b32_e32 v38, 0xffff0000, v85
	v_mul_f32_e32 v35, v34, v35
	v_mul_f32_e32 v36, v34, v36
	v_mul_f32_e32 v37, v34, v37
	v_mul_f32_e32 v38, v34, v38
	v_fma_f32 v64, v24, v35, v64
	v_fma_f32 v65, v25, v36, v65
	v_fma_f32 v66, v26, v37, v66
	v_fma_f32 v67, v27, v38, v67
	global_store_dwordx4 v166, v[64:67], s[24:25] offset:2048
	v_cvt_pk_bf16_f32 v84, v64, v65
	v_cvt_pk_bf16_f32 v85, v66, v67
	global_store_dwordx2 v32, v[84:85], s[26:27] offset:3072
	s_waitcnt vmcnt(47)
	v_lshlrev_b32_e32 v35, 16, v86
	v_and_b32_e32 v36, 0xffff0000, v86
	v_lshlrev_b32_e32 v37, 16, v87
	v_and_b32_e32 v38, 0xffff0000, v87
	v_mul_f32_e32 v35, v34, v35
	v_mul_f32_e32 v36, v34, v36
	v_mul_f32_e32 v37, v34, v37
	v_mul_f32_e32 v38, v34, v38
	v_fma_f32 v68, v28, v35, v68
	v_fma_f32 v69, v29, v36, v69
	v_fma_f32 v70, v30, v37, v70
	v_fma_f32 v71, v31, v38, v71
	global_store_dwordx4 v166, v[68:71], s[24:25] offset:3072
	v_cvt_pk_bf16_f32 v86, v68, v69
	v_cvt_pk_bf16_f32 v87, v70, v71
	global_store_dwordx2 v32, v[86:87], s[26:27] offset:3584
	s_add_i32 s80, s80, s82
	s_cmpk_gt_i32 s80, 0x7fff
	s_cbranch_scc1 .Lp7b_done
	s_branch .Lp7b_loop
.Lp7b_done:
.LBB0_1492:
	s_waitcnt vmcnt(0)
	s_barrier
	s_mov_b64 s[6:7], exec
	v_readlane_b32 s8, v246, 0
	v_readlane_b32 s9, v246, 1
	s_and_b64 s[8:9], s[6:7], s[8:9]
	s_mov_b64 exec, s[8:9]
	s_cbranch_execz .LBB0_1544
	s_add_i32 s8, 0, 0x20040
	v_mov_b32_e32 v0, s8
	s_waitcnt vmcnt(0) expcnt(0) lgkmcnt(0)
	ds_read_b32 v2, v0
	s_add_i32 s8, 0, 0x20044
	v_mov_b32_e32 v0, s8
	ds_read_b32 v0, v0
	s_waitcnt lgkmcnt(1)
	v_cmp_ne_u32_e32 vcc, 0, v2
	s_cbranch_vccnz .LBB0_1508
	v_readlane_b32 s8, v246, 2
	v_readlane_b32 s9, v246, 3
	s_mul_i32 s33, s9, s3
	s_mul_i32 s33, s33, s8
	s_add_u32 s8, s74, 0xc0200
	s_addc_u32 s9, s75, 0
	s_add_u32 s10, s74, 0xc0400
	s_addc_u32 s11, s75, 0
	s_add_u32 s12, s74, 0xc0500
	s_addc_u32 s13, s75, 0
	s_add_u32 s14, s74, 0xc0600
	s_addc_u32 s15, s75, 0
	s_add_u32 s16, s74, 0xc0700
	s_addc_u32 s17, s75, 0
	s_add_u32 s18, s74, 0xc0800
	s_addc_u32 s19, s75, 0
	s_add_u32 s20, s74, 0xc0900
	s_addc_u32 s21, s75, 0
	s_add_u32 s22, s74, 0xc0a00
	s_addc_u32 s23, s75, 0
	s_add_u32 s24, s74, 0xc0b00
	s_addc_u32 s25, s75, 0
	s_add_u32 s26, s74, 0xc0c00
	s_addc_u32 s27, s75, 0
	s_add_u32 s28, s74, 0xc0d00
	s_addc_u32 s29, s75, 0
	s_add_u32 s30, s74, 0xc0e00
	s_addc_u32 s31, s75, 0
	s_add_u32 s34, s74, 0xc0f00
	s_addc_u32 s35, s75, 0
	s_add_u32 s36, s74, 0xc1000
	s_addc_u32 s37, s75, 0
	s_add_u32 s38, s74, 0xc1100
	s_addc_u32 s39, s75, 0
	s_add_u32 s40, s74, 0xc1200
	s_addc_u32 s41, s75, 0
	s_add_u32 s42, s74, 0xc1300
	s_addc_u32 s43, s75, 0
	s_mov_b32 s50, 1
	v_mov_b32_e32 v16, 0
	s_branch .LBB0_1496
